# speedup vs baseline: 1.0080x; 1.0080x over previous
; template <int DH, int MODE>
; __device__ void attn_item(const Params& p, int layer, int b, int blk, int head, char* smem) {
;     ...
;         const int kpb = ktok + half * 32;
;         float run = 0.f;
; #pragma unroll 2
;         for (int c = 7; c >= 0; --c) {
;           float4 v = s4[c];
;           float e[4] = {v.x, v.y, v.z, v.w};
; #pragma unroll
;           for (int k = 3; k >= 0; --k) {
;             float z = e[k];
;             bool valid = (kpb + c * 4 + k) < qpos;
;             float sp = fmaxf(z, 0.f) + __builtin_amdgcn_logf(1.f + __builtin_amdgcn_exp2f(-fabsf(z)));
;             run += valid ? -sp : 0.f;
;             e[k] = z + run;
;           }
;           s4[c] = make_float4(e[0], e[1], e[2], e[3]);
.LBB0_203:
	s_or_b64 exec, exec, s[50:51]
	s_add_i32 s26, s84, 1
	s_min_i32 s50, s26, s82
	s_sub_i32 s50, s82, s50
	s_lshl_b32 s50, s50, 6
	s_ashr_i32 s51, s50, 31
	s_add_u32 s50, s50, s81
	s_addc_u32 s51, s51, 0
	s_waitcnt lgkmcnt(0)
	s_barrier
	ds_write_b16 v171, v96
	ds_write_b16_d16_hi v171, v96 offset:64
	ds_write_b16 v171, v97 offset:128
	ds_write_b16_d16_hi v171, v97 offset:192
	ds_write_b16 v171, v98 offset:256
	ds_write_b16_d16_hi v171, v98 offset:320
	ds_write_b16 v171, v99 offset:384
	ds_write_b16_d16_hi v171, v99 offset:448
	ds_write_b16 v171, v100 offset:2048
	ds_write_b16_d16_hi v171, v100 offset:2112
	ds_write_b16 v171, v101 offset:2176
	ds_write_b16_d16_hi v171, v101 offset:2240
	ds_write_b16 v171, v102 offset:2304
	ds_write_b16_d16_hi v171, v102 offset:2368
	ds_write_b16 v171, v103 offset:2432
	ds_write_b16_d16_hi v171, v103 offset:2496
	s_waitcnt vmcnt(1)
	ds_write_b16 v171, v108 offset:4096
	ds_write_b16_d16_hi v171, v108 offset:4160
	ds_write_b16 v171, v109 offset:4224
	ds_write_b16_d16_hi v171, v109 offset:4288
	ds_write_b16 v171, v110 offset:4352
	ds_write_b16_d16_hi v171, v110 offset:4416
	ds_write_b16 v171, v111 offset:4480
	ds_write_b16_d16_hi v171, v111 offset:4544
	s_waitcnt vmcnt(0)
	ds_write_b16 v171, v104 offset:6144
	ds_write_b16_d16_hi v171, v104 offset:6208
	ds_write_b16 v171, v105 offset:6272
	ds_write_b16_d16_hi v171, v105 offset:6336
	ds_write_b16 v171, v106 offset:6400
	ds_write_b16_d16_hi v171, v106 offset:6464
	ds_write_b16 v171, v107 offset:6528
	ds_write_b16_d16_hi v171, v107 offset:6592
	v_lshl_add_u64 v[96:97], s[50:51], 0, v[134:135]
	v_mad_u64_u32 v[104:105], s[52:53], v96, s55, v[140:141]
	v_or_b32_e32 v96, s50, v132
	v_mad_i32_i24 v105, v97, s55, v105
	v_mad_u64_u32 v[106:107], s[52:53], v96, s55, v[142:143]
	v_add_co_u32_e32 v96, vcc, s69, v104
	v_mad_i32_i24 v107, s51, v160, v107
	s_nop 0
	v_addc_co_u32_e32 v97, vcc, 0, v105, vcc
	v_add_co_u32_e32 v98, vcc, 0x4c000, v104
	s_nop 1
	v_addc_co_u32_e32 v99, vcc, 0, v105, vcc
	v_add_co_u32_e32 v100, vcc, 0x72000, v104
	global_load_dwordx4 v[120:123], v[96:97], off
	global_load_dwordx4 v[116:119], v[98:99], off
	v_addc_co_u32_e32 v101, vcc, 0, v105, vcc
	global_load_dwordx4 v[96:99], v[106:107], off
	global_load_dwordx4 v[124:127], v[100:101], off
	s_nop 0
	global_load_dwordx4 v[100:103], v[106:107], off offset:64
	global_load_dwordx4 v[108:111], v[106:107], off offset:128
	global_load_dwordx4 v[112:115], v[104:105], off
	s_nop 0
	global_load_dwordx4 v[104:107], v[106:107], off offset:192
	s_and_saveexec_b64 s[50:51], s[8:9]
	s_cbranch_execz .LBB0_214
	v_mov_b32_e32 v146, 0
	s_mov_b32 s52, 0
	v_mov_b32_e32 v148, v166
	s_setprio 1
	ds_read_b128 v[208:211], v167 offset:112
	ds_read_b128 v[204:207], v167 offset:96
	ds_read_b128 v[200:203], v167 offset:80
	ds_read_b128 v[196:199], v167 offset:64
	ds_read_b128 v[192:195], v167 offset:48
	ds_read_b128 v[188:191], v167 offset:32
	ds_read_b128 v[184:187], v167 offset:16
	ds_read_b128 v[180:183], v167
	v_sub_u32_e32 v212, v144, v173
	v_add_u32_e32 v212, 0xffffc040, v212
	v_cmp_lt_i32_e32 vcc, 31, v212
	s_cmp_eq_u64 vcc, exec
	s_cbranch_scc1 .Lsb_p1fast_3
	s_waitcnt lgkmcnt(7)
	v_exp_f32_e64 v213, -|v211|
	v_exp_f32_e64 v214, -|v210|
	v_exp_f32_e64 v215, -|v209|
	v_max_f32_e32 v216, 0, v211
	v_max_f32_e32 v217, 0, v210
	v_max_f32_e32 v218, 0, v209
	v_add_f32_e32 v213, 1.0, v213
	v_add_f32_e32 v214, 1.0, v214
	v_add_f32_e32 v215, 1.0, v215
	v_log_f32_e32 v213, v213
	v_log_f32_e32 v214, v214
	v_log_f32_e32 v215, v215
	v_cmp_lt_i32_e32 vcc, 31, v212
	v_cmp_lt_i32_e64 s[92:93], 30, v212
	v_cmp_lt_i32_e64 s[94:95], 29, v212
	v_add_f32_e32 v213, v216, v213
	v_add_f32_e32 v214, v217, v214
	v_add_f32_e32 v215, v218, v215
	v_cndmask_b32_e64 v213, 0, -v213, vcc
	v_cndmask_b32_e64 v214, 0, -v214, s[92:93]
	v_cndmask_b32_e64 v215, 0, -v215, s[94:95]
	v_add_f32_e32 v146, v146, v213
	v_add_f32_e32 v211, v211, v146
	v_add_f32_e32 v146, v146, v214
	v_add_f32_e32 v210, v210, v146
	v_add_f32_e32 v146, v146, v215
	v_add_f32_e32 v209, v209, v146
	s_waitcnt lgkmcnt(6)
	v_exp_f32_e64 v213, -|v208|
	v_exp_f32_e64 v214, -|v207|
	v_exp_f32_e64 v215, -|v206|
	v_max_f32_e32 v216, 0, v208
	v_max_f32_e32 v217, 0, v207
	v_max_f32_e32 v218, 0, v206
	v_add_f32_e32 v213, 1.0, v213
	v_add_f32_e32 v214, 1.0, v214
	v_add_f32_e32 v215, 1.0, v215
	v_log_f32_e32 v213, v213
	v_log_f32_e32 v214, v214
	v_log_f32_e32 v215, v215
	v_cmp_lt_i32_e32 vcc, 28, v212
	v_cmp_lt_i32_e64 s[92:93], 27, v212
	v_cmp_lt_i32_e64 s[94:95], 26, v212
	v_add_f32_e32 v213, v216, v213
	v_add_f32_e32 v214, v217, v214
	v_add_f32_e32 v215, v218, v215
	v_cndmask_b32_e64 v213, 0, -v213, vcc
	v_cndmask_b32_e64 v214, 0, -v214, s[92:93]
	v_cndmask_b32_e64 v215, 0, -v215, s[94:95]
	v_add_f32_e32 v146, v146, v213
	v_add_f32_e32 v208, v208, v146
	v_add_f32_e32 v146, v146, v214
	v_add_f32_e32 v207, v207, v146
	v_add_f32_e32 v146, v146, v215
	v_add_f32_e32 v206, v206, v146
	s_waitcnt lgkmcnt(5)
; template <int DH, int MODE>
; __device__ void attn_item(const Params& p, int layer, int b, int blk, int head, char* smem) {
;     ...
;         const int qpos = blk * 128 + row;
;         const int kpb = ktok + half * 32;
;         float run = 0.f;
; #pragma unroll 2
;         for (int c = 7; c >= 0; --c) {
;           float4 v = s4[c];
;           float e[4] = {v.x, v.y, v.z, v.w};
; #pragma unroll
;           for (int k = 3; k >= 0; --k) {
;             float z = e[k];
;             bool valid = (kpb + c * 4 + k) < qpos;
;             float sp = fmaxf(z, 0.f) + __builtin_amdgcn_logf(1.f + __builtin_amdgcn_exp2f(-fabsf(z)));
;             run += valid ? -sp : 0.f;
;             e[k] = z + run;
;           }
;           s4[c] = make_float4(e[0], e[1], e[2], e[3]);
;         }
	v_exp_f32_e64 v213, -|v205|
	v_exp_f32_e64 v214, -|v204|
	v_exp_f32_e64 v215, -|v203|
	v_max_f32_e32 v216, 0, v205
	v_max_f32_e32 v217, 0, v204
	v_max_f32_e32 v218, 0, v203
	v_add_f32_e32 v213, 1.0, v213
	v_add_f32_e32 v214, 1.0, v214
	v_add_f32_e32 v215, 1.0, v215
	v_log_f32_e32 v213, v213
	v_log_f32_e32 v214, v214
	v_log_f32_e32 v215, v215
	v_cmp_lt_i32_e32 vcc, 25, v212
	v_cmp_lt_i32_e64 s[92:93], 24, v212
	v_cmp_lt_i32_e64 s[94:95], 23, v212
	v_add_f32_e32 v213, v216, v213
	v_add_f32_e32 v214, v217, v214
	v_add_f32_e32 v215, v218, v215
	v_cndmask_b32_e64 v213, 0, -v213, vcc
	v_cndmask_b32_e64 v214, 0, -v214, s[92:93]
	v_cndmask_b32_e64 v215, 0, -v215, s[94:95]
	v_add_f32_e32 v146, v146, v213
	v_add_f32_e32 v205, v205, v146
	v_add_f32_e32 v146, v146, v214
	v_add_f32_e32 v204, v204, v146
	v_add_f32_e32 v146, v146, v215
	v_add_f32_e32 v203, v203, v146
	v_exp_f32_e64 v213, -|v202|
	v_exp_f32_e64 v214, -|v201|
	v_exp_f32_e64 v215, -|v200|
	v_max_f32_e32 v216, 0, v202
	v_max_f32_e32 v217, 0, v201
	v_max_f32_e32 v218, 0, v200
	v_add_f32_e32 v213, 1.0, v213
	v_add_f32_e32 v214, 1.0, v214
	v_add_f32_e32 v215, 1.0, v215
	v_log_f32_e32 v213, v213
	v_log_f32_e32 v214, v214
	v_log_f32_e32 v215, v215
	v_cmp_lt_i32_e32 vcc, 22, v212
	v_cmp_lt_i32_e64 s[92:93], 21, v212
	v_cmp_lt_i32_e64 s[94:95], 20, v212
	v_add_f32_e32 v213, v216, v213
	v_add_f32_e32 v214, v217, v214
	v_add_f32_e32 v215, v218, v215
	v_cndmask_b32_e64 v213, 0, -v213, vcc
	v_cndmask_b32_e64 v214, 0, -v214, s[92:93]
	v_cndmask_b32_e64 v215, 0, -v215, s[94:95]
	v_add_f32_e32 v146, v146, v213
	v_add_f32_e32 v202, v202, v146
	v_add_f32_e32 v146, v146, v214
	v_add_f32_e32 v201, v201, v146
	v_add_f32_e32 v146, v146, v215
	v_add_f32_e32 v200, v200, v146
	s_waitcnt lgkmcnt(4)
	v_exp_f32_e64 v213, -|v199|
	v_exp_f32_e64 v214, -|v198|
	v_exp_f32_e64 v215, -|v197|
	v_max_f32_e32 v216, 0, v199
	v_max_f32_e32 v217, 0, v198
	v_max_f32_e32 v218, 0, v197
	v_add_f32_e32 v213, 1.0, v213
	v_add_f32_e32 v214, 1.0, v214
	v_add_f32_e32 v215, 1.0, v215
	v_log_f32_e32 v213, v213
	v_log_f32_e32 v214, v214
	v_log_f32_e32 v215, v215
	v_cmp_lt_i32_e32 vcc, 19, v212
	v_cmp_lt_i32_e64 s[92:93], 18, v212
	v_cmp_lt_i32_e64 s[94:95], 17, v212
	v_add_f32_e32 v213, v216, v213
	v_add_f32_e32 v214, v217, v214
	v_add_f32_e32 v215, v218, v215
	v_cndmask_b32_e64 v213, 0, -v213, vcc
	v_cndmask_b32_e64 v214, 0, -v214, s[92:93]
	v_cndmask_b32_e64 v215, 0, -v215, s[94:95]
	v_add_f32_e32 v146, v146, v213
	v_add_f32_e32 v199, v199, v146
	v_add_f32_e32 v146, v146, v214
	v_add_f32_e32 v198, v198, v146
	v_add_f32_e32 v146, v146, v215
	v_add_f32_e32 v197, v197, v146
	s_waitcnt lgkmcnt(3)
	v_exp_f32_e64 v213, -|v196|
	v_exp_f32_e64 v214, -|v195|
	v_exp_f32_e64 v215, -|v194|
	v_max_f32_e32 v216, 0, v196
	v_max_f32_e32 v217, 0, v195
	v_max_f32_e32 v218, 0, v194
	v_add_f32_e32 v213, 1.0, v213
	v_add_f32_e32 v214, 1.0, v214
	v_add_f32_e32 v215, 1.0, v215
	v_log_f32_e32 v213, v213
	v_log_f32_e32 v214, v214
	v_log_f32_e32 v215, v215
	v_cmp_lt_i32_e32 vcc, 16, v212
	v_cmp_lt_i32_e64 s[92:93], 15, v212
	v_cmp_lt_i32_e64 s[94:95], 14, v212
	v_add_f32_e32 v213, v216, v213
	v_add_f32_e32 v214, v217, v214
	v_add_f32_e32 v215, v218, v215
	v_cndmask_b32_e64 v213, 0, -v213, vcc
	v_cndmask_b32_e64 v214, 0, -v214, s[92:93]
	v_cndmask_b32_e64 v215, 0, -v215, s[94:95]
	v_add_f32_e32 v146, v146, v213
	v_add_f32_e32 v196, v196, v146
	v_add_f32_e32 v146, v146, v214
	v_add_f32_e32 v195, v195, v146
	v_add_f32_e32 v146, v146, v215
	v_add_f32_e32 v194, v194, v146
	s_waitcnt lgkmcnt(2)
; template <int DH, int MODE>
; __device__ void attn_item(const Params& p, int layer, int b, int blk, int head, char* smem) {
;     ...
;         const int qpos = blk * 128 + row;
;         const int kpb = ktok + half * 32;
;         float run = 0.f;
; #pragma unroll 2
;         for (int c = 7; c >= 0; --c) {
;           float4 v = s4[c];
;           float e[4] = {v.x, v.y, v.z, v.w};
; #pragma unroll
;           for (int k = 3; k >= 0; --k) {
;             float z = e[k];
;             bool valid = (kpb + c * 4 + k) < qpos;
;             float sp = fmaxf(z, 0.f) + __builtin_amdgcn_logf(1.f + __builtin_amdgcn_exp2f(-fabsf(z)));
;             run += valid ? -sp : 0.f;
;             e[k] = z + run;
;           }
;           s4[c] = make_float4(e[0], e[1], e[2], e[3]);
;         }
	v_exp_f32_e64 v213, -|v193|
	v_exp_f32_e64 v214, -|v192|
	v_exp_f32_e64 v215, -|v191|
	v_max_f32_e32 v216, 0, v193
	v_max_f32_e32 v217, 0, v192
	v_max_f32_e32 v218, 0, v191
	v_add_f32_e32 v213, 1.0, v213
	v_add_f32_e32 v214, 1.0, v214
	v_add_f32_e32 v215, 1.0, v215
	v_log_f32_e32 v213, v213
	v_log_f32_e32 v214, v214
	v_log_f32_e32 v215, v215
	v_cmp_lt_i32_e32 vcc, 13, v212
	v_cmp_lt_i32_e64 s[92:93], 12, v212
	v_cmp_lt_i32_e64 s[94:95], 11, v212
	v_add_f32_e32 v213, v216, v213
	v_add_f32_e32 v214, v217, v214
	v_add_f32_e32 v215, v218, v215
	v_cndmask_b32_e64 v213, 0, -v213, vcc
	v_cndmask_b32_e64 v214, 0, -v214, s[92:93]
	v_cndmask_b32_e64 v215, 0, -v215, s[94:95]
	v_add_f32_e32 v146, v146, v213
	v_add_f32_e32 v193, v193, v146
	v_add_f32_e32 v146, v146, v214
	v_add_f32_e32 v192, v192, v146
	v_add_f32_e32 v146, v146, v215
	v_add_f32_e32 v191, v191, v146
	v_exp_f32_e64 v213, -|v190|
	v_exp_f32_e64 v214, -|v189|
	v_exp_f32_e64 v215, -|v188|
	v_max_f32_e32 v216, 0, v190
	v_max_f32_e32 v217, 0, v189
	v_max_f32_e32 v218, 0, v188
	v_add_f32_e32 v213, 1.0, v213
	v_add_f32_e32 v214, 1.0, v214
	v_add_f32_e32 v215, 1.0, v215
	v_log_f32_e32 v213, v213
	v_log_f32_e32 v214, v214
	v_log_f32_e32 v215, v215
	v_cmp_lt_i32_e32 vcc, 10, v212
	v_cmp_lt_i32_e64 s[92:93], 9, v212
	v_cmp_lt_i32_e64 s[94:95], 8, v212
	v_add_f32_e32 v213, v216, v213
	v_add_f32_e32 v214, v217, v214
	v_add_f32_e32 v215, v218, v215
	v_cndmask_b32_e64 v213, 0, -v213, vcc
	v_cndmask_b32_e64 v214, 0, -v214, s[92:93]
	v_cndmask_b32_e64 v215, 0, -v215, s[94:95]
	v_add_f32_e32 v146, v146, v213
	v_add_f32_e32 v190, v190, v146
	v_add_f32_e32 v146, v146, v214
	v_add_f32_e32 v189, v189, v146
	v_add_f32_e32 v146, v146, v215
	v_add_f32_e32 v188, v188, v146
	s_waitcnt lgkmcnt(1)
	v_exp_f32_e64 v213, -|v187|
	v_exp_f32_e64 v214, -|v186|
	v_exp_f32_e64 v215, -|v185|
	v_max_f32_e32 v216, 0, v187
	v_max_f32_e32 v217, 0, v186
	v_max_f32_e32 v218, 0, v185
	v_add_f32_e32 v213, 1.0, v213
	v_add_f32_e32 v214, 1.0, v214
	v_add_f32_e32 v215, 1.0, v215
	v_log_f32_e32 v213, v213
	v_log_f32_e32 v214, v214
	v_log_f32_e32 v215, v215
	v_cmp_lt_i32_e32 vcc, 7, v212
	v_cmp_lt_i32_e64 s[92:93], 6, v212
	v_cmp_lt_i32_e64 s[94:95], 5, v212
	v_add_f32_e32 v213, v216, v213
	v_add_f32_e32 v214, v217, v214
	v_add_f32_e32 v215, v218, v215
	v_cndmask_b32_e64 v213, 0, -v213, vcc
	v_cndmask_b32_e64 v214, 0, -v214, s[92:93]
	v_cndmask_b32_e64 v215, 0, -v215, s[94:95]
	v_add_f32_e32 v146, v146, v213
	v_add_f32_e32 v187, v187, v146
	v_add_f32_e32 v146, v146, v214
	v_add_f32_e32 v186, v186, v146
	v_add_f32_e32 v146, v146, v215
	v_add_f32_e32 v185, v185, v146
	s_waitcnt lgkmcnt(0)
	v_exp_f32_e64 v213, -|v184|
	v_exp_f32_e64 v214, -|v183|
	v_exp_f32_e64 v215, -|v182|
	v_max_f32_e32 v216, 0, v184
	v_max_f32_e32 v217, 0, v183
	v_max_f32_e32 v218, 0, v182
	v_add_f32_e32 v213, 1.0, v213
	v_add_f32_e32 v214, 1.0, v214
	v_add_f32_e32 v215, 1.0, v215
	v_log_f32_e32 v213, v213
	v_log_f32_e32 v214, v214
	v_log_f32_e32 v215, v215
	v_cmp_lt_i32_e32 vcc, 4, v212
	v_cmp_lt_i32_e64 s[92:93], 3, v212
	v_cmp_lt_i32_e64 s[94:95], 2, v212
	v_add_f32_e32 v213, v216, v213
	v_add_f32_e32 v214, v217, v214
	v_add_f32_e32 v215, v218, v215
	v_cndmask_b32_e64 v213, 0, -v213, vcc
	v_cndmask_b32_e64 v214, 0, -v214, s[92:93]
	v_cndmask_b32_e64 v215, 0, -v215, s[94:95]
	v_add_f32_e32 v146, v146, v213
	v_add_f32_e32 v184, v184, v146
	v_add_f32_e32 v146, v146, v214
	v_add_f32_e32 v183, v183, v146
	v_add_f32_e32 v146, v146, v215
	v_add_f32_e32 v182, v182, v146
	v_exp_f32_e64 v213, -|v181|
	v_exp_f32_e64 v214, -|v180|
	v_max_f32_e32 v216, 0, v181
	v_max_f32_e32 v217, 0, v180
	v_add_f32_e32 v213, 1.0, v213
	v_add_f32_e32 v214, 1.0, v214
	v_log_f32_e32 v213, v213
	v_log_f32_e32 v214, v214
	v_cmp_lt_i32_e32 vcc, 1, v212
	v_cmp_lt_i32_e64 s[92:93], 0, v212
	s_nop 0
	v_add_f32_e32 v213, v216, v213
	v_add_f32_e32 v214, v217, v214
	v_cndmask_b32_e64 v213, 0, -v213, vcc
	v_cndmask_b32_e64 v214, 0, -v214, s[92:93]
	v_add_f32_e32 v146, v146, v213
	v_add_f32_e32 v181, v181, v146
	v_add_f32_e32 v146, v146, v214
	v_add_f32_e32 v180, v180, v146
	s_branch .Lsb_p1done_3

; __device__ __forceinline__ unsigned pack2(float a, float b) { return (unsigned)f2bf(a) | ((unsigned)f2bf(b) << 16); }
; template <int DH, int MODE>
; __device__ void attn_item(const Params& p, int layer, int b, int blk, int head, char* smem) {
;     ...
;         float other = __shfl_xor(run, 1);
;         float offs = m_run + (half == 0 ? other : 0.f);
; #pragma unroll 2
;         for (int s8 = 0; s8 < 4; ++s8) {
;           float4 va = s4[2 * s8], vb = s4[2 * s8 + 1];
;           float e[8] = {va.x, va.y, va.z, va.w, vb.x, vb.y, vb.z, vb.w};
;           float pv[8];
; #pragma unroll
;           for (int k = 0; k < 8; ++k) {
;             bool valid = (kpb + s8 * 8 + k) < qpos;
;             pv[k] = valid ? __builtin_amdgcn_exp2f(e[k] + offs) : 0.f;
;           }
;           uint4 ov;
;           ov.x = pack2(pv[0], pv[1]); ov.y = pack2(pv[2], pv[3]);
;           ov.z = pack2(pv[4], pv[5]); ov.w = pack2(pv[6], pv[7]);
;           *reinterpret_cast<uint4*>(prow + s8 * 16) = ov;
;         }
.Lsb_p1done_3:
	s_setprio 0
	ds_bpermute_b32 v147, v163, v146
	s_mov_b32 s85, 0
	v_mov_b32_e32 v175, v168
	v_mov_b32_e32 v177, v167
	s_waitcnt lgkmcnt(0)
	v_cndmask_b32_e64 v148, 0, v147, s[6:7]
	v_add_f32_e32 v176, v174, v148
	v_sub_u32_e32 v212, v144, v173
	v_add_u32_e32 v212, 0xffffc040, v212
	v_cmp_lt_i32_e32 vcc, 31, v212
	s_cmp_eq_u64 vcc, exec
	s_cbranch_scc1 .Lsb_p2fast_3
	v_add_f32_e32 v180, v176, v180
	v_add_f32_e32 v181, v176, v181
	v_add_f32_e32 v182, v176, v182
	v_exp_f32_e32 v180, v180
	v_exp_f32_e32 v181, v181
	v_exp_f32_e32 v182, v182
	v_cmp_lt_i32_e32 vcc, 0, v212
	v_cmp_lt_i32_e64 s[92:93], 1, v212
	v_cmp_lt_i32_e64 s[94:95], 2, v212
	v_cndmask_b32_e32 v180, 0, v180, vcc
	v_cndmask_b32_e64 v181, 0, v181, s[92:93]
	v_cndmask_b32_e64 v182, 0, v182, s[94:95]
	v_add_f32_e32 v183, v176, v183
	v_add_f32_e32 v184, v176, v184
	v_add_f32_e32 v185, v176, v185
	v_exp_f32_e32 v183, v183
	v_exp_f32_e32 v184, v184
	v_exp_f32_e32 v185, v185
	v_cmp_lt_i32_e32 vcc, 3, v212
	v_cmp_lt_i32_e64 s[92:93], 4, v212
	v_cmp_lt_i32_e64 s[94:95], 5, v212
	v_cndmask_b32_e32 v183, 0, v183, vcc
	v_cndmask_b32_e64 v184, 0, v184, s[92:93]
	v_cndmask_b32_e64 v185, 0, v185, s[94:95]
	v_add_f32_e32 v186, v176, v186
	v_add_f32_e32 v187, v176, v187
	v_add_f32_e32 v188, v176, v188
	v_exp_f32_e32 v186, v186
	v_exp_f32_e32 v187, v187
	v_exp_f32_e32 v188, v188
	v_cmp_lt_i32_e32 vcc, 6, v212
	v_cmp_lt_i32_e64 s[92:93], 7, v212
	v_cmp_lt_i32_e64 s[94:95], 8, v212
	v_cndmask_b32_e32 v186, 0, v186, vcc
	v_cndmask_b32_e64 v187, 0, v187, s[92:93]
	v_cndmask_b32_e64 v188, 0, v188, s[94:95]
	v_add_f32_e32 v189, v176, v189
	v_add_f32_e32 v190, v176, v190
	v_add_f32_e32 v191, v176, v191
	v_exp_f32_e32 v189, v189
	v_exp_f32_e32 v190, v190
	v_exp_f32_e32 v191, v191
	v_cmp_lt_i32_e32 vcc, 9, v212
	v_cmp_lt_i32_e64 s[92:93], 10, v212
	v_cmp_lt_i32_e64 s[94:95], 11, v212
	v_cndmask_b32_e32 v189, 0, v189, vcc
	v_cndmask_b32_e64 v190, 0, v190, s[92:93]
	v_cndmask_b32_e64 v191, 0, v191, s[94:95]
	v_add_f32_e32 v192, v176, v192
	v_add_f32_e32 v193, v176, v193
	v_add_f32_e32 v194, v176, v194
	v_exp_f32_e32 v192, v192
	v_exp_f32_e32 v193, v193
	v_exp_f32_e32 v194, v194
	v_cmp_lt_i32_e32 vcc, 12, v212
	v_cmp_lt_i32_e64 s[92:93], 13, v212
	v_cmp_lt_i32_e64 s[94:95], 14, v212
	v_cndmask_b32_e32 v192, 0, v192, vcc
	v_cndmask_b32_e64 v193, 0, v193, s[92:93]
	v_cndmask_b32_e64 v194, 0, v194, s[94:95]
	v_add_f32_e32 v195, v176, v195
	v_add_f32_e32 v196, v176, v196
	v_add_f32_e32 v197, v176, v197
	v_exp_f32_e32 v195, v195
	v_exp_f32_e32 v196, v196
	v_exp_f32_e32 v197, v197
	v_cmp_lt_i32_e32 vcc, 15, v212
	v_cmp_lt_i32_e64 s[92:93], 16, v212
	v_cmp_lt_i32_e64 s[94:95], 17, v212
	v_cndmask_b32_e32 v195, 0, v195, vcc
	v_cndmask_b32_e64 v196, 0, v196, s[92:93]
	v_cndmask_b32_e64 v197, 0, v197, s[94:95]
	v_add_f32_e32 v198, v176, v198
	v_add_f32_e32 v199, v176, v199
	v_add_f32_e32 v200, v176, v200
	v_exp_f32_e32 v198, v198
	v_exp_f32_e32 v199, v199
	v_exp_f32_e32 v200, v200
	v_cmp_lt_i32_e32 vcc, 18, v212
	v_cmp_lt_i32_e64 s[92:93], 19, v212
	v_cmp_lt_i32_e64 s[94:95], 20, v212
	v_cndmask_b32_e32 v198, 0, v198, vcc
	v_cndmask_b32_e64 v199, 0, v199, s[92:93]
	v_cndmask_b32_e64 v200, 0, v200, s[94:95]
	v_add_f32_e32 v201, v176, v201
	v_add_f32_e32 v202, v176, v202
	v_add_f32_e32 v203, v176, v203
	v_exp_f32_e32 v201, v201
	v_exp_f32_e32 v202, v202
	v_exp_f32_e32 v203, v203
	v_cmp_lt_i32_e32 vcc, 21, v212
	v_cmp_lt_i32_e64 s[92:93], 22, v212
	v_cmp_lt_i32_e64 s[94:95], 23, v212
	v_cndmask_b32_e32 v201, 0, v201, vcc
	v_cndmask_b32_e64 v202, 0, v202, s[92:93]
	v_cndmask_b32_e64 v203, 0, v203, s[94:95]
	v_add_f32_e32 v204, v176, v204
	v_add_f32_e32 v205, v176, v205
	v_add_f32_e32 v206, v176, v206
	v_exp_f32_e32 v204, v204
	v_exp_f32_e32 v205, v205
	v_exp_f32_e32 v206, v206
	v_cmp_lt_i32_e32 vcc, 24, v212
	v_cmp_lt_i32_e64 s[92:93], 25, v212
	v_cmp_lt_i32_e64 s[94:95], 26, v212
	v_cndmask_b32_e32 v204, 0, v204, vcc
	v_cndmask_b32_e64 v205, 0, v205, s[92:93]
	v_cndmask_b32_e64 v206, 0, v206, s[94:95]
	v_add_f32_e32 v207, v176, v207
	v_add_f32_e32 v208, v176, v208
	v_add_f32_e32 v209, v176, v209
	v_exp_f32_e32 v207, v207
	v_exp_f32_e32 v208, v208
	v_exp_f32_e32 v209, v209
	v_cmp_lt_i32_e32 vcc, 27, v212
	v_cmp_lt_i32_e64 s[92:93], 28, v212
	v_cmp_lt_i32_e64 s[94:95], 29, v212
	v_cndmask_b32_e32 v207, 0, v207, vcc
	v_cndmask_b32_e64 v208, 0, v208, s[92:93]
	v_cndmask_b32_e64 v209, 0, v209, s[94:95]
	v_add_f32_e32 v210, v176, v210
	v_add_f32_e32 v211, v176, v211
	v_exp_f32_e32 v210, v210
	v_exp_f32_e32 v211, v211
	v_cmp_lt_i32_e32 vcc, 30, v212
	v_cmp_lt_i32_e64 s[92:93], 31, v212
	s_nop 0
	v_cndmask_b32_e32 v210, 0, v210, vcc
	v_cndmask_b32_e64 v211, 0, v211, s[92:93]
	v_cvt_pk_bf16_f32 v148, v180, v181
	v_cvt_pk_bf16_f32 v149, v182, v183
	v_cvt_pk_bf16_f32 v150, v184, v185
	v_cvt_pk_bf16_f32 v151, v186, v187
	ds_write_b128 v175, v[148:151]
	s_nop 0
	v_cvt_pk_bf16_f32 v148, v188, v189
	v_cvt_pk_bf16_f32 v149, v190, v191
	v_cvt_pk_bf16_f32 v150, v192, v193
	v_cvt_pk_bf16_f32 v151, v194, v195
	ds_write_b128 v175, v[148:151] offset:16
	s_nop 0
	v_cvt_pk_bf16_f32 v148, v196, v197
	v_cvt_pk_bf16_f32 v149, v198, v199
	v_cvt_pk_bf16_f32 v150, v200, v201
	v_cvt_pk_bf16_f32 v151, v202, v203
	ds_write_b128 v175, v[148:151] offset:32
	s_nop 0
	v_cvt_pk_bf16_f32 v148, v204, v205
	v_cvt_pk_bf16_f32 v149, v206, v207
	v_cvt_pk_bf16_f32 v150, v208, v209
	v_cvt_pk_bf16_f32 v151, v210, v211
	ds_write_b128 v175, v[148:151] offset:48
	s_branch .LBB0_213

; template <int DH, int MODE>
; __device__ void attn_item(const Params& p, int layer, int b, int blk, int head, char* smem) {
;     ...
;         const int qpos = blk * 128 + row;
;         const int kpb = ktok + half * 32;
;         float run = 0.f;
; #pragma unroll 2
;         for (int c = 7; c >= 0; --c) {
;           float4 v = s4[c];
;           float e[4] = {v.x, v.y, v.z, v.w};
; #pragma unroll
;           for (int k = 3; k >= 0; --k) {
;             float z = e[k];
;             bool valid = (kpb + c * 4 + k) < qpos;
;             float sp = fmaxf(z, 0.f) + __builtin_amdgcn_logf(1.f + __builtin_amdgcn_exp2f(-fabsf(z)));
;             run += valid ? -sp : 0.f;
;             e[k] = z + run;
;           }
;           s4[c] = make_float4(e[0], e[1], e[2], e[3]);
;         }
.LBB0_524:
	s_or_b64 exec, exec, s[52:53]
	s_add_i32 s36, s87, 1
	s_min_i32 s52, s36, s85
	s_sub_i32 s52, s85, s52
	s_lshl_b32 s52, s52, 6
	s_ashr_i32 s53, s52, 31
	s_add_u32 s52, s52, s84
	s_addc_u32 s53, s53, 0
	s_waitcnt lgkmcnt(0)
	s_barrier
	ds_write_b16 v171, v96
	ds_write_b16_d16_hi v171, v96 offset:64
	ds_write_b16 v171, v97 offset:128
	ds_write_b16_d16_hi v171, v97 offset:192
	ds_write_b16 v171, v98 offset:256
	ds_write_b16_d16_hi v171, v98 offset:320
	ds_write_b16 v171, v99 offset:384
	ds_write_b16_d16_hi v171, v99 offset:448
	ds_write_b16 v171, v100 offset:2048
	ds_write_b16_d16_hi v171, v100 offset:2112
	ds_write_b16 v171, v101 offset:2176
	ds_write_b16_d16_hi v171, v101 offset:2240
	ds_write_b16 v171, v102 offset:2304
	ds_write_b16_d16_hi v171, v102 offset:2368
	ds_write_b16 v171, v103 offset:2432
	ds_write_b16_d16_hi v171, v103 offset:2496
	s_waitcnt vmcnt(1)
	ds_write_b16 v171, v108 offset:4096
	ds_write_b16_d16_hi v171, v108 offset:4160
	ds_write_b16 v171, v109 offset:4224
	ds_write_b16_d16_hi v171, v109 offset:4288
	ds_write_b16 v171, v110 offset:4352
	ds_write_b16_d16_hi v171, v110 offset:4416
	ds_write_b16 v171, v111 offset:4480
	ds_write_b16_d16_hi v171, v111 offset:4544
	s_waitcnt vmcnt(0)
	ds_write_b16 v171, v104 offset:6144
	ds_write_b16_d16_hi v171, v104 offset:6208
	ds_write_b16 v171, v105 offset:6272
	ds_write_b16_d16_hi v171, v105 offset:6336
	ds_write_b16 v171, v106 offset:6400
	ds_write_b16_d16_hi v171, v106 offset:6464
	ds_write_b16 v171, v107 offset:6528
	ds_write_b16_d16_hi v171, v107 offset:6592
	v_lshl_add_u64 v[96:97], s[52:53], 0, v[134:135]
	v_mad_u64_u32 v[104:105], s[54:55], v96, s63, v[140:141]
	v_or_b32_e32 v96, s52, v132
	v_mad_i32_i24 v105, v97, s63, v105
	v_mad_u64_u32 v[106:107], s[54:55], v96, s63, v[142:143]
	v_add_co_u32_e32 v96, vcc, s71, v104
	v_mad_i32_i24 v107, s53, v160, v107
	s_nop 0
	v_addc_co_u32_e32 v97, vcc, 0, v105, vcc
	v_add_co_u32_e32 v98, vcc, 0x4c000, v104
	s_nop 1
	v_addc_co_u32_e32 v99, vcc, 0, v105, vcc
	v_add_co_u32_e32 v100, vcc, 0x72000, v104
	global_load_dwordx4 v[120:123], v[96:97], off
	global_load_dwordx4 v[116:119], v[98:99], off
	v_addc_co_u32_e32 v101, vcc, 0, v105, vcc
	global_load_dwordx4 v[96:99], v[106:107], off
	global_load_dwordx4 v[124:127], v[100:101], off
	s_nop 0
	global_load_dwordx4 v[100:103], v[106:107], off offset:64
	global_load_dwordx4 v[108:111], v[106:107], off offset:128
	global_load_dwordx4 v[112:115], v[104:105], off
	s_nop 0
	global_load_dwordx4 v[104:107], v[106:107], off offset:192
	s_and_saveexec_b64 s[52:53], s[16:17]
	s_cbranch_execz .LBB0_535
	v_mov_b32_e32 v146, 0
	s_mov_b32 s54, 0
	v_mov_b32_e32 v148, v166
	s_setprio 1
	ds_read_b128 v[208:211], v167 offset:112
	ds_read_b128 v[204:207], v167 offset:96
	ds_read_b128 v[200:203], v167 offset:80
	ds_read_b128 v[196:199], v167 offset:64
	ds_read_b128 v[192:195], v167 offset:48
	ds_read_b128 v[188:191], v167 offset:32
	ds_read_b128 v[184:187], v167 offset:16
	ds_read_b128 v[180:183], v167
	v_sub_u32_e32 v212, v144, v173
	v_add_u32_e32 v212, 0xffffc040, v212
	v_cmp_lt_i32_e32 vcc, 31, v212
	s_cmp_eq_u64 vcc, exec
	s_cbranch_scc1 .Lsb_p1fast_2
	s_waitcnt lgkmcnt(7)
	v_exp_f32_e64 v213, -|v211|
	v_exp_f32_e64 v214, -|v210|
	v_exp_f32_e64 v215, -|v209|
	v_max_f32_e32 v216, 0, v211
	v_max_f32_e32 v217, 0, v210
	v_max_f32_e32 v218, 0, v209
	v_add_f32_e32 v213, 1.0, v213
	v_add_f32_e32 v214, 1.0, v214
	v_add_f32_e32 v215, 1.0, v215
	v_log_f32_e32 v213, v213
	v_log_f32_e32 v214, v214
	v_log_f32_e32 v215, v215
	v_cmp_lt_i32_e32 vcc, 31, v212
	v_cmp_lt_i32_e64 s[92:93], 30, v212
	v_cmp_lt_i32_e64 s[94:95], 29, v212
	v_add_f32_e32 v213, v216, v213
	v_add_f32_e32 v214, v217, v214
	v_add_f32_e32 v215, v218, v215
	v_cndmask_b32_e64 v213, 0, -v213, vcc
	v_cndmask_b32_e64 v214, 0, -v214, s[92:93]
	v_cndmask_b32_e64 v215, 0, -v215, s[94:95]
	v_add_f32_e32 v146, v146, v213
	v_add_f32_e32 v211, v211, v146
	v_add_f32_e32 v146, v146, v214
	v_add_f32_e32 v210, v210, v146
	v_add_f32_e32 v146, v146, v215
	v_add_f32_e32 v209, v209, v146
	s_waitcnt lgkmcnt(6)
	v_exp_f32_e64 v213, -|v208|
	v_exp_f32_e64 v214, -|v207|
	v_exp_f32_e64 v215, -|v206|
	v_max_f32_e32 v216, 0, v208
	v_max_f32_e32 v217, 0, v207
	v_max_f32_e32 v218, 0, v206
	v_add_f32_e32 v213, 1.0, v213
	v_add_f32_e32 v214, 1.0, v214
	v_add_f32_e32 v215, 1.0, v215
	v_log_f32_e32 v213, v213
	v_log_f32_e32 v214, v214
	v_log_f32_e32 v215, v215
	v_cmp_lt_i32_e32 vcc, 28, v212
	v_cmp_lt_i32_e64 s[92:93], 27, v212
	v_cmp_lt_i32_e64 s[94:95], 26, v212
	v_add_f32_e32 v213, v216, v213
	v_add_f32_e32 v214, v217, v214
	v_add_f32_e32 v215, v218, v215
	v_cndmask_b32_e64 v213, 0, -v213, vcc
	v_cndmask_b32_e64 v214, 0, -v214, s[92:93]
	v_cndmask_b32_e64 v215, 0, -v215, s[94:95]
	v_add_f32_e32 v146, v146, v213
	v_add_f32_e32 v208, v208, v146
	v_add_f32_e32 v146, v146, v214
	v_add_f32_e32 v207, v207, v146
	v_add_f32_e32 v146, v146, v215
	v_add_f32_e32 v206, v206, v146
	s_waitcnt lgkmcnt(5)
; template <int DH, int MODE>
; __device__ void attn_item(const Params& p, int layer, int b, int blk, int head, char* smem) {
;     ...
;         const int qpos = blk * 128 + row;
;         const int kpb = ktok + half * 32;
;         float run = 0.f;
; #pragma unroll 2
;         for (int c = 7; c >= 0; --c) {
;           float4 v = s4[c];
;           float e[4] = {v.x, v.y, v.z, v.w};
; #pragma unroll
;           for (int k = 3; k >= 0; --k) {
;             float z = e[k];
;             bool valid = (kpb + c * 4 + k) < qpos;
;             float sp = fmaxf(z, 0.f) + __builtin_amdgcn_logf(1.f + __builtin_amdgcn_exp2f(-fabsf(z)));
;             run += valid ? -sp : 0.f;
;             e[k] = z + run;
;           }
;           s4[c] = make_float4(e[0], e[1], e[2], e[3]);
;         }
	v_exp_f32_e64 v213, -|v205|
	v_exp_f32_e64 v214, -|v204|
	v_exp_f32_e64 v215, -|v203|
	v_max_f32_e32 v216, 0, v205
	v_max_f32_e32 v217, 0, v204
	v_max_f32_e32 v218, 0, v203
	v_add_f32_e32 v213, 1.0, v213
	v_add_f32_e32 v214, 1.0, v214
	v_add_f32_e32 v215, 1.0, v215
	v_log_f32_e32 v213, v213
	v_log_f32_e32 v214, v214
	v_log_f32_e32 v215, v215
	v_cmp_lt_i32_e32 vcc, 25, v212
	v_cmp_lt_i32_e64 s[92:93], 24, v212
	v_cmp_lt_i32_e64 s[94:95], 23, v212
	v_add_f32_e32 v213, v216, v213
	v_add_f32_e32 v214, v217, v214
	v_add_f32_e32 v215, v218, v215
	v_cndmask_b32_e64 v213, 0, -v213, vcc
	v_cndmask_b32_e64 v214, 0, -v214, s[92:93]
	v_cndmask_b32_e64 v215, 0, -v215, s[94:95]
	v_add_f32_e32 v146, v146, v213
	v_add_f32_e32 v205, v205, v146
	v_add_f32_e32 v146, v146, v214
	v_add_f32_e32 v204, v204, v146
	v_add_f32_e32 v146, v146, v215
	v_add_f32_e32 v203, v203, v146
	v_exp_f32_e64 v213, -|v202|
	v_exp_f32_e64 v214, -|v201|
	v_exp_f32_e64 v215, -|v200|
	v_max_f32_e32 v216, 0, v202
	v_max_f32_e32 v217, 0, v201
	v_max_f32_e32 v218, 0, v200
	v_add_f32_e32 v213, 1.0, v213
	v_add_f32_e32 v214, 1.0, v214
	v_add_f32_e32 v215, 1.0, v215
	v_log_f32_e32 v213, v213
	v_log_f32_e32 v214, v214
	v_log_f32_e32 v215, v215
	v_cmp_lt_i32_e32 vcc, 22, v212
	v_cmp_lt_i32_e64 s[92:93], 21, v212
	v_cmp_lt_i32_e64 s[94:95], 20, v212
	v_add_f32_e32 v213, v216, v213
	v_add_f32_e32 v214, v217, v214
	v_add_f32_e32 v215, v218, v215
	v_cndmask_b32_e64 v213, 0, -v213, vcc
	v_cndmask_b32_e64 v214, 0, -v214, s[92:93]
	v_cndmask_b32_e64 v215, 0, -v215, s[94:95]
	v_add_f32_e32 v146, v146, v213
	v_add_f32_e32 v202, v202, v146
	v_add_f32_e32 v146, v146, v214
	v_add_f32_e32 v201, v201, v146
	v_add_f32_e32 v146, v146, v215
	v_add_f32_e32 v200, v200, v146
	s_waitcnt lgkmcnt(4)
	v_exp_f32_e64 v213, -|v199|
	v_exp_f32_e64 v214, -|v198|
	v_exp_f32_e64 v215, -|v197|
	v_max_f32_e32 v216, 0, v199
	v_max_f32_e32 v217, 0, v198
	v_max_f32_e32 v218, 0, v197
	v_add_f32_e32 v213, 1.0, v213
	v_add_f32_e32 v214, 1.0, v214
	v_add_f32_e32 v215, 1.0, v215
	v_log_f32_e32 v213, v213
	v_log_f32_e32 v214, v214
	v_log_f32_e32 v215, v215
	v_cmp_lt_i32_e32 vcc, 19, v212
	v_cmp_lt_i32_e64 s[92:93], 18, v212
	v_cmp_lt_i32_e64 s[94:95], 17, v212
	v_add_f32_e32 v213, v216, v213
	v_add_f32_e32 v214, v217, v214
	v_add_f32_e32 v215, v218, v215
	v_cndmask_b32_e64 v213, 0, -v213, vcc
	v_cndmask_b32_e64 v214, 0, -v214, s[92:93]
	v_cndmask_b32_e64 v215, 0, -v215, s[94:95]
	v_add_f32_e32 v146, v146, v213
	v_add_f32_e32 v199, v199, v146
	v_add_f32_e32 v146, v146, v214
	v_add_f32_e32 v198, v198, v146
	v_add_f32_e32 v146, v146, v215
	v_add_f32_e32 v197, v197, v146
	s_waitcnt lgkmcnt(3)
	v_exp_f32_e64 v213, -|v196|
	v_exp_f32_e64 v214, -|v195|
	v_exp_f32_e64 v215, -|v194|
	v_max_f32_e32 v216, 0, v196
	v_max_f32_e32 v217, 0, v195
	v_max_f32_e32 v218, 0, v194
	v_add_f32_e32 v213, 1.0, v213
	v_add_f32_e32 v214, 1.0, v214
	v_add_f32_e32 v215, 1.0, v215
	v_log_f32_e32 v213, v213
	v_log_f32_e32 v214, v214
	v_log_f32_e32 v215, v215
	v_cmp_lt_i32_e32 vcc, 16, v212
	v_cmp_lt_i32_e64 s[92:93], 15, v212
	v_cmp_lt_i32_e64 s[94:95], 14, v212
	v_add_f32_e32 v213, v216, v213
	v_add_f32_e32 v214, v217, v214
	v_add_f32_e32 v215, v218, v215
	v_cndmask_b32_e64 v213, 0, -v213, vcc
	v_cndmask_b32_e64 v214, 0, -v214, s[92:93]
	v_cndmask_b32_e64 v215, 0, -v215, s[94:95]
	v_add_f32_e32 v146, v146, v213
	v_add_f32_e32 v196, v196, v146
	v_add_f32_e32 v146, v146, v214
	v_add_f32_e32 v195, v195, v146
	v_add_f32_e32 v146, v146, v215
	v_add_f32_e32 v194, v194, v146
	s_waitcnt lgkmcnt(2)
; template <int DH, int MODE>
; __device__ void attn_item(const Params& p, int layer, int b, int blk, int head, char* smem) {
;     ...
;         const int qpos = blk * 128 + row;
;         const int kpb = ktok + half * 32;
;         float run = 0.f;
; #pragma unroll 2
;         for (int c = 7; c >= 0; --c) {
;           float4 v = s4[c];
;           float e[4] = {v.x, v.y, v.z, v.w};
; #pragma unroll
;           for (int k = 3; k >= 0; --k) {
;             float z = e[k];
;             bool valid = (kpb + c * 4 + k) < qpos;
;             float sp = fmaxf(z, 0.f) + __builtin_amdgcn_logf(1.f + __builtin_amdgcn_exp2f(-fabsf(z)));
;             run += valid ? -sp : 0.f;
;             e[k] = z + run;
;           }
;           s4[c] = make_float4(e[0], e[1], e[2], e[3]);
;         }
	v_exp_f32_e64 v213, -|v193|
	v_exp_f32_e64 v214, -|v192|
	v_exp_f32_e64 v215, -|v191|
	v_max_f32_e32 v216, 0, v193
	v_max_f32_e32 v217, 0, v192
	v_max_f32_e32 v218, 0, v191
	v_add_f32_e32 v213, 1.0, v213
	v_add_f32_e32 v214, 1.0, v214
	v_add_f32_e32 v215, 1.0, v215
	v_log_f32_e32 v213, v213
	v_log_f32_e32 v214, v214
	v_log_f32_e32 v215, v215
	v_cmp_lt_i32_e32 vcc, 13, v212
	v_cmp_lt_i32_e64 s[92:93], 12, v212
	v_cmp_lt_i32_e64 s[94:95], 11, v212
	v_add_f32_e32 v213, v216, v213
	v_add_f32_e32 v214, v217, v214
	v_add_f32_e32 v215, v218, v215
	v_cndmask_b32_e64 v213, 0, -v213, vcc
	v_cndmask_b32_e64 v214, 0, -v214, s[92:93]
	v_cndmask_b32_e64 v215, 0, -v215, s[94:95]
	v_add_f32_e32 v146, v146, v213
	v_add_f32_e32 v193, v193, v146
	v_add_f32_e32 v146, v146, v214
	v_add_f32_e32 v192, v192, v146
	v_add_f32_e32 v146, v146, v215
	v_add_f32_e32 v191, v191, v146
	v_exp_f32_e64 v213, -|v190|
	v_exp_f32_e64 v214, -|v189|
	v_exp_f32_e64 v215, -|v188|
	v_max_f32_e32 v216, 0, v190
	v_max_f32_e32 v217, 0, v189
	v_max_f32_e32 v218, 0, v188
	v_add_f32_e32 v213, 1.0, v213
	v_add_f32_e32 v214, 1.0, v214
	v_add_f32_e32 v215, 1.0, v215
	v_log_f32_e32 v213, v213
	v_log_f32_e32 v214, v214
	v_log_f32_e32 v215, v215
	v_cmp_lt_i32_e32 vcc, 10, v212
	v_cmp_lt_i32_e64 s[92:93], 9, v212
	v_cmp_lt_i32_e64 s[94:95], 8, v212
	v_add_f32_e32 v213, v216, v213
	v_add_f32_e32 v214, v217, v214
	v_add_f32_e32 v215, v218, v215
	v_cndmask_b32_e64 v213, 0, -v213, vcc
	v_cndmask_b32_e64 v214, 0, -v214, s[92:93]
	v_cndmask_b32_e64 v215, 0, -v215, s[94:95]
	v_add_f32_e32 v146, v146, v213
	v_add_f32_e32 v190, v190, v146
	v_add_f32_e32 v146, v146, v214
	v_add_f32_e32 v189, v189, v146
	v_add_f32_e32 v146, v146, v215
	v_add_f32_e32 v188, v188, v146
	s_waitcnt lgkmcnt(1)
	v_exp_f32_e64 v213, -|v187|
	v_exp_f32_e64 v214, -|v186|
	v_exp_f32_e64 v215, -|v185|
	v_max_f32_e32 v216, 0, v187
	v_max_f32_e32 v217, 0, v186
	v_max_f32_e32 v218, 0, v185
	v_add_f32_e32 v213, 1.0, v213
	v_add_f32_e32 v214, 1.0, v214
	v_add_f32_e32 v215, 1.0, v215
	v_log_f32_e32 v213, v213
	v_log_f32_e32 v214, v214
	v_log_f32_e32 v215, v215
	v_cmp_lt_i32_e32 vcc, 7, v212
	v_cmp_lt_i32_e64 s[92:93], 6, v212
	v_cmp_lt_i32_e64 s[94:95], 5, v212
	v_add_f32_e32 v213, v216, v213
	v_add_f32_e32 v214, v217, v214
	v_add_f32_e32 v215, v218, v215
	v_cndmask_b32_e64 v213, 0, -v213, vcc
	v_cndmask_b32_e64 v214, 0, -v214, s[92:93]
	v_cndmask_b32_e64 v215, 0, -v215, s[94:95]
	v_add_f32_e32 v146, v146, v213
	v_add_f32_e32 v187, v187, v146
	v_add_f32_e32 v146, v146, v214
	v_add_f32_e32 v186, v186, v146
	v_add_f32_e32 v146, v146, v215
	v_add_f32_e32 v185, v185, v146
	s_waitcnt lgkmcnt(0)
	v_exp_f32_e64 v213, -|v184|
	v_exp_f32_e64 v214, -|v183|
	v_exp_f32_e64 v215, -|v182|
	v_max_f32_e32 v216, 0, v184
	v_max_f32_e32 v217, 0, v183
	v_max_f32_e32 v218, 0, v182
	v_add_f32_e32 v213, 1.0, v213
	v_add_f32_e32 v214, 1.0, v214
	v_add_f32_e32 v215, 1.0, v215
	v_log_f32_e32 v213, v213
	v_log_f32_e32 v214, v214
	v_log_f32_e32 v215, v215
	v_cmp_lt_i32_e32 vcc, 4, v212
	v_cmp_lt_i32_e64 s[92:93], 3, v212
	v_cmp_lt_i32_e64 s[94:95], 2, v212
	v_add_f32_e32 v213, v216, v213
	v_add_f32_e32 v214, v217, v214
	v_add_f32_e32 v215, v218, v215
	v_cndmask_b32_e64 v213, 0, -v213, vcc
	v_cndmask_b32_e64 v214, 0, -v214, s[92:93]
	v_cndmask_b32_e64 v215, 0, -v215, s[94:95]
	v_add_f32_e32 v146, v146, v213
	v_add_f32_e32 v184, v184, v146
	v_add_f32_e32 v146, v146, v214
	v_add_f32_e32 v183, v183, v146
	v_add_f32_e32 v146, v146, v215
	v_add_f32_e32 v182, v182, v146
	v_exp_f32_e64 v213, -|v181|
	v_exp_f32_e64 v214, -|v180|
	v_max_f32_e32 v216, 0, v181
	v_max_f32_e32 v217, 0, v180
	v_add_f32_e32 v213, 1.0, v213
	v_add_f32_e32 v214, 1.0, v214
	v_log_f32_e32 v213, v213
	v_log_f32_e32 v214, v214
	v_cmp_lt_i32_e32 vcc, 1, v212
	v_cmp_lt_i32_e64 s[92:93], 0, v212
	s_nop 0
	v_add_f32_e32 v213, v216, v213
	v_add_f32_e32 v214, v217, v214
	v_cndmask_b32_e64 v213, 0, -v213, vcc
	v_cndmask_b32_e64 v214, 0, -v214, s[92:93]
	v_add_f32_e32 v146, v146, v213
	v_add_f32_e32 v181, v181, v146
	v_add_f32_e32 v146, v146, v214
	v_add_f32_e32 v180, v180, v146
	s_branch .Lsb_p1done_2

; __device__ __forceinline__ unsigned pack2(float a, float b) { return (unsigned)f2bf(a) | ((unsigned)f2bf(b) << 16); }
; template <int DH, int MODE>
; __device__ void attn_item(const Params& p, int layer, int b, int blk, int head, char* smem) {
;     ...
;         float other = __shfl_xor(run, 1);
;         float offs = m_run + (half == 0 ? other : 0.f);
; #pragma unroll 2
;         for (int s8 = 0; s8 < 4; ++s8) {
;           float4 va = s4[2 * s8], vb = s4[2 * s8 + 1];
;           float e[8] = {va.x, va.y, va.z, va.w, vb.x, vb.y, vb.z, vb.w};
;           float pv[8];
; #pragma unroll
;           for (int k = 0; k < 8; ++k) {
;             bool valid = (kpb + s8 * 8 + k) < qpos;
;             pv[k] = valid ? __builtin_amdgcn_exp2f(e[k] + offs) : 0.f;
;           }
;           uint4 ov;
;           ov.x = pack2(pv[0], pv[1]); ov.y = pack2(pv[2], pv[3]);
;           ov.z = pack2(pv[4], pv[5]); ov.w = pack2(pv[6], pv[7]);
;           *reinterpret_cast<uint4*>(prow + s8 * 16) = ov;
;         }
.Lsb_p1done_2:
	s_setprio 0
	ds_bpermute_b32 v147, v163, v146
	s_mov_b32 s88, 0
	v_mov_b32_e32 v175, v168
	v_mov_b32_e32 v177, v167
	s_waitcnt lgkmcnt(0)
	v_cndmask_b32_e64 v148, 0, v147, s[14:15]
	v_add_f32_e32 v176, v174, v148
	v_sub_u32_e32 v212, v144, v173
	v_add_u32_e32 v212, 0xffffc040, v212
	v_cmp_lt_i32_e32 vcc, 31, v212
	s_cmp_eq_u64 vcc, exec
	s_cbranch_scc1 .Lsb_p2fast_2
	v_add_f32_e32 v180, v176, v180
	v_add_f32_e32 v181, v176, v181
	v_add_f32_e32 v182, v176, v182
	v_exp_f32_e32 v180, v180
	v_exp_f32_e32 v181, v181
	v_exp_f32_e32 v182, v182
	v_cmp_lt_i32_e32 vcc, 0, v212
	v_cmp_lt_i32_e64 s[92:93], 1, v212
	v_cmp_lt_i32_e64 s[94:95], 2, v212
	v_cndmask_b32_e32 v180, 0, v180, vcc
	v_cndmask_b32_e64 v181, 0, v181, s[92:93]
	v_cndmask_b32_e64 v182, 0, v182, s[94:95]
	v_add_f32_e32 v183, v176, v183
	v_add_f32_e32 v184, v176, v184
	v_add_f32_e32 v185, v176, v185
	v_exp_f32_e32 v183, v183
	v_exp_f32_e32 v184, v184
	v_exp_f32_e32 v185, v185
	v_cmp_lt_i32_e32 vcc, 3, v212
	v_cmp_lt_i32_e64 s[92:93], 4, v212
	v_cmp_lt_i32_e64 s[94:95], 5, v212
	v_cndmask_b32_e32 v183, 0, v183, vcc
	v_cndmask_b32_e64 v184, 0, v184, s[92:93]
	v_cndmask_b32_e64 v185, 0, v185, s[94:95]
	v_add_f32_e32 v186, v176, v186
	v_add_f32_e32 v187, v176, v187
	v_add_f32_e32 v188, v176, v188
	v_exp_f32_e32 v186, v186
	v_exp_f32_e32 v187, v187
	v_exp_f32_e32 v188, v188
	v_cmp_lt_i32_e32 vcc, 6, v212
	v_cmp_lt_i32_e64 s[92:93], 7, v212
	v_cmp_lt_i32_e64 s[94:95], 8, v212
	v_cndmask_b32_e32 v186, 0, v186, vcc
	v_cndmask_b32_e64 v187, 0, v187, s[92:93]
	v_cndmask_b32_e64 v188, 0, v188, s[94:95]
	v_add_f32_e32 v189, v176, v189
	v_add_f32_e32 v190, v176, v190
	v_add_f32_e32 v191, v176, v191
	v_exp_f32_e32 v189, v189
	v_exp_f32_e32 v190, v190
	v_exp_f32_e32 v191, v191
	v_cmp_lt_i32_e32 vcc, 9, v212
	v_cmp_lt_i32_e64 s[92:93], 10, v212
	v_cmp_lt_i32_e64 s[94:95], 11, v212
	v_cndmask_b32_e32 v189, 0, v189, vcc
	v_cndmask_b32_e64 v190, 0, v190, s[92:93]
	v_cndmask_b32_e64 v191, 0, v191, s[94:95]
	v_add_f32_e32 v192, v176, v192
	v_add_f32_e32 v193, v176, v193
	v_add_f32_e32 v194, v176, v194
	v_exp_f32_e32 v192, v192
	v_exp_f32_e32 v193, v193
	v_exp_f32_e32 v194, v194
	v_cmp_lt_i32_e32 vcc, 12, v212
	v_cmp_lt_i32_e64 s[92:93], 13, v212
	v_cmp_lt_i32_e64 s[94:95], 14, v212
	v_cndmask_b32_e32 v192, 0, v192, vcc
	v_cndmask_b32_e64 v193, 0, v193, s[92:93]
	v_cndmask_b32_e64 v194, 0, v194, s[94:95]
	v_add_f32_e32 v195, v176, v195
	v_add_f32_e32 v196, v176, v196
	v_add_f32_e32 v197, v176, v197
	v_exp_f32_e32 v195, v195
	v_exp_f32_e32 v196, v196
	v_exp_f32_e32 v197, v197
	v_cmp_lt_i32_e32 vcc, 15, v212
	v_cmp_lt_i32_e64 s[92:93], 16, v212
	v_cmp_lt_i32_e64 s[94:95], 17, v212
	v_cndmask_b32_e32 v195, 0, v195, vcc
	v_cndmask_b32_e64 v196, 0, v196, s[92:93]
	v_cndmask_b32_e64 v197, 0, v197, s[94:95]
	v_add_f32_e32 v198, v176, v198
	v_add_f32_e32 v199, v176, v199
	v_add_f32_e32 v200, v176, v200
	v_exp_f32_e32 v198, v198
	v_exp_f32_e32 v199, v199
	v_exp_f32_e32 v200, v200
	v_cmp_lt_i32_e32 vcc, 18, v212
	v_cmp_lt_i32_e64 s[92:93], 19, v212
	v_cmp_lt_i32_e64 s[94:95], 20, v212
	v_cndmask_b32_e32 v198, 0, v198, vcc
	v_cndmask_b32_e64 v199, 0, v199, s[92:93]
	v_cndmask_b32_e64 v200, 0, v200, s[94:95]
	v_add_f32_e32 v201, v176, v201
	v_add_f32_e32 v202, v176, v202
	v_add_f32_e32 v203, v176, v203
	v_exp_f32_e32 v201, v201
	v_exp_f32_e32 v202, v202
	v_exp_f32_e32 v203, v203
	v_cmp_lt_i32_e32 vcc, 21, v212
	v_cmp_lt_i32_e64 s[92:93], 22, v212
	v_cmp_lt_i32_e64 s[94:95], 23, v212
	v_cndmask_b32_e32 v201, 0, v201, vcc
	v_cndmask_b32_e64 v202, 0, v202, s[92:93]
	v_cndmask_b32_e64 v203, 0, v203, s[94:95]
	v_add_f32_e32 v204, v176, v204
	v_add_f32_e32 v205, v176, v205
	v_add_f32_e32 v206, v176, v206
	v_exp_f32_e32 v204, v204
	v_exp_f32_e32 v205, v205
	v_exp_f32_e32 v206, v206
	v_cmp_lt_i32_e32 vcc, 24, v212
	v_cmp_lt_i32_e64 s[92:93], 25, v212
	v_cmp_lt_i32_e64 s[94:95], 26, v212
	v_cndmask_b32_e32 v204, 0, v204, vcc
	v_cndmask_b32_e64 v205, 0, v205, s[92:93]
	v_cndmask_b32_e64 v206, 0, v206, s[94:95]
	v_add_f32_e32 v207, v176, v207
	v_add_f32_e32 v208, v176, v208
	v_add_f32_e32 v209, v176, v209
	v_exp_f32_e32 v207, v207
	v_exp_f32_e32 v208, v208
	v_exp_f32_e32 v209, v209
	v_cmp_lt_i32_e32 vcc, 27, v212
	v_cmp_lt_i32_e64 s[92:93], 28, v212
	v_cmp_lt_i32_e64 s[94:95], 29, v212
	v_cndmask_b32_e32 v207, 0, v207, vcc
	v_cndmask_b32_e64 v208, 0, v208, s[92:93]
	v_cndmask_b32_e64 v209, 0, v209, s[94:95]
	v_add_f32_e32 v210, v176, v210
	v_add_f32_e32 v211, v176, v211
	v_exp_f32_e32 v210, v210
	v_exp_f32_e32 v211, v211
	v_cmp_lt_i32_e32 vcc, 30, v212
	v_cmp_lt_i32_e64 s[92:93], 31, v212
	s_nop 0
	v_cndmask_b32_e32 v210, 0, v210, vcc
	v_cndmask_b32_e64 v211, 0, v211, s[92:93]
	v_cvt_pk_bf16_f32 v148, v180, v181
	v_cvt_pk_bf16_f32 v149, v182, v183
	v_cvt_pk_bf16_f32 v150, v184, v185
	v_cvt_pk_bf16_f32 v151, v186, v187
	ds_write_b128 v175, v[148:151]
	s_nop 0
	v_cvt_pk_bf16_f32 v148, v188, v189
	v_cvt_pk_bf16_f32 v149, v190, v191
	v_cvt_pk_bf16_f32 v150, v192, v193
	v_cvt_pk_bf16_f32 v151, v194, v195
	ds_write_b128 v175, v[148:151] offset:16
	s_nop 0
	v_cvt_pk_bf16_f32 v148, v196, v197
	v_cvt_pk_bf16_f32 v149, v198, v199
	v_cvt_pk_bf16_f32 v150, v200, v201
	v_cvt_pk_bf16_f32 v151, v202, v203
	ds_write_b128 v175, v[148:151] offset:32
	s_nop 0
	v_cvt_pk_bf16_f32 v148, v204, v205
	v_cvt_pk_bf16_f32 v149, v206, v207
	v_cvt_pk_bf16_f32 v150, v208, v209
	v_cvt_pk_bf16_f32 v151, v210, v211
	ds_write_b128 v175, v[148:151] offset:48
	s_branch .LBB0_534

; template <int DH, int MODE>
; __device__ void attn_item(const Params& p, int layer, int b, int blk, int head, char* smem) {
;     ...
;         const int qpos = blk * 128 + row;
;         const int kpb = ktok + half * 32;
;         float run = 0.f;
; #pragma unroll 2
;         for (int c = 7; c >= 0; --c) {
;           float4 v = s4[c];
;           float e[4] = {v.x, v.y, v.z, v.w};
; #pragma unroll
;           for (int k = 3; k >= 0; --k) {
;             float z = e[k];
;             bool valid = (kpb + c * 4 + k) < qpos;
;             float sp = fmaxf(z, 0.f) + __builtin_amdgcn_logf(1.f + __builtin_amdgcn_exp2f(-fabsf(z)));
;             run += valid ? -sp : 0.f;
;             e[k] = z + run;
;           }
;           s4[c] = make_float4(e[0], e[1], e[2], e[3]);
;         }
.LBB0_845:
	s_or_b64 exec, exec, s[50:51]
	s_add_i32 s36, s87, 1
	s_min_i32 s50, s36, s85
	s_sub_i32 s50, s85, s50
	s_lshl_b32 s50, s50, 6
	s_ashr_i32 s51, s50, 31
	s_add_u32 s50, s50, s84
	s_addc_u32 s51, s51, 0
	s_waitcnt lgkmcnt(0)
	s_barrier
	ds_write_b16 v171, v96
	ds_write_b16_d16_hi v171, v96 offset:64
	ds_write_b16 v171, v97 offset:128
	ds_write_b16_d16_hi v171, v97 offset:192
	ds_write_b16 v171, v98 offset:256
	ds_write_b16_d16_hi v171, v98 offset:320
	ds_write_b16 v171, v99 offset:384
	ds_write_b16_d16_hi v171, v99 offset:448
	ds_write_b16 v171, v100 offset:2048
	ds_write_b16_d16_hi v171, v100 offset:2112
	ds_write_b16 v171, v101 offset:2176
	ds_write_b16_d16_hi v171, v101 offset:2240
	ds_write_b16 v171, v102 offset:2304
	ds_write_b16_d16_hi v171, v102 offset:2368
	ds_write_b16 v171, v103 offset:2432
	ds_write_b16_d16_hi v171, v103 offset:2496
	s_waitcnt vmcnt(1)
	ds_write_b16 v171, v108 offset:4096
	ds_write_b16_d16_hi v171, v108 offset:4160
	ds_write_b16 v171, v109 offset:4224
	ds_write_b16_d16_hi v171, v109 offset:4288
	ds_write_b16 v171, v110 offset:4352
	ds_write_b16_d16_hi v171, v110 offset:4416
	ds_write_b16 v171, v111 offset:4480
	ds_write_b16_d16_hi v171, v111 offset:4544
	s_waitcnt vmcnt(0)
	ds_write_b16 v171, v104 offset:6144
	ds_write_b16_d16_hi v171, v104 offset:6208
	ds_write_b16 v171, v105 offset:6272
	ds_write_b16_d16_hi v171, v105 offset:6336
	ds_write_b16 v171, v106 offset:6400
	ds_write_b16_d16_hi v171, v106 offset:6464
	ds_write_b16 v171, v107 offset:6528
	ds_write_b16_d16_hi v171, v107 offset:6592
	v_lshl_add_u64 v[96:97], s[50:51], 0, v[134:135]
	v_mad_u64_u32 v[104:105], s[52:53], v96, s45, v[140:141]
	v_or_b32_e32 v96, s50, v132
	v_mad_i32_i24 v105, v97, s45, v105
	v_mad_u64_u32 v[106:107], s[52:53], v96, s45, v[142:143]
	v_add_co_u32_e32 v96, vcc, s71, v104
	v_mad_i32_i24 v107, s51, v160, v107
	s_nop 0
	v_addc_co_u32_e32 v97, vcc, 0, v105, vcc
	v_add_co_u32_e32 v98, vcc, 0x4c000, v104
	s_nop 1
	v_addc_co_u32_e32 v99, vcc, 0, v105, vcc
	v_add_co_u32_e32 v100, vcc, 0x72000, v104
	global_load_dwordx4 v[120:123], v[96:97], off
	global_load_dwordx4 v[116:119], v[98:99], off
	v_addc_co_u32_e32 v101, vcc, 0, v105, vcc
	global_load_dwordx4 v[96:99], v[106:107], off
	global_load_dwordx4 v[124:127], v[100:101], off
	s_nop 0
	global_load_dwordx4 v[100:103], v[106:107], off offset:64
	global_load_dwordx4 v[108:111], v[106:107], off offset:128
	global_load_dwordx4 v[112:115], v[104:105], off
	s_nop 0
	global_load_dwordx4 v[104:107], v[106:107], off offset:192
	s_and_saveexec_b64 s[50:51], s[16:17]
	s_cbranch_execz .LBB0_856
	v_mov_b32_e32 v146, 0
	s_mov_b32 s52, 0
	v_mov_b32_e32 v148, v166
	s_setprio 1
	ds_read_b128 v[208:211], v167 offset:112
	ds_read_b128 v[204:207], v167 offset:96
	ds_read_b128 v[200:203], v167 offset:80
	ds_read_b128 v[196:199], v167 offset:64
	ds_read_b128 v[192:195], v167 offset:48
	ds_read_b128 v[188:191], v167 offset:32
	ds_read_b128 v[184:187], v167 offset:16
	ds_read_b128 v[180:183], v167
	v_sub_u32_e32 v212, v144, v173
	v_add_u32_e32 v212, 0xffffc040, v212
	v_cmp_lt_i32_e32 vcc, 31, v212
	s_cmp_eq_u64 vcc, exec
	s_cbranch_scc1 .Lsb_p1fast_1
	s_waitcnt lgkmcnt(7)
	v_exp_f32_e64 v213, -|v211|
	v_exp_f32_e64 v214, -|v210|
	v_exp_f32_e64 v215, -|v209|
	v_max_f32_e32 v216, 0, v211
	v_max_f32_e32 v217, 0, v210
	v_max_f32_e32 v218, 0, v209
	v_add_f32_e32 v213, 1.0, v213
	v_add_f32_e32 v214, 1.0, v214
	v_add_f32_e32 v215, 1.0, v215
	v_log_f32_e32 v213, v213
	v_log_f32_e32 v214, v214
	v_log_f32_e32 v215, v215
	v_cmp_lt_i32_e32 vcc, 31, v212
	v_cmp_lt_i32_e64 s[92:93], 30, v212
	v_cmp_lt_i32_e64 s[94:95], 29, v212
	v_add_f32_e32 v213, v216, v213
	v_add_f32_e32 v214, v217, v214
	v_add_f32_e32 v215, v218, v215
	v_cndmask_b32_e64 v213, 0, -v213, vcc
	v_cndmask_b32_e64 v214, 0, -v214, s[92:93]
	v_cndmask_b32_e64 v215, 0, -v215, s[94:95]
	v_add_f32_e32 v146, v146, v213
	v_add_f32_e32 v211, v211, v146
	v_add_f32_e32 v146, v146, v214
	v_add_f32_e32 v210, v210, v146
	v_add_f32_e32 v146, v146, v215
	v_add_f32_e32 v209, v209, v146
	s_waitcnt lgkmcnt(6)
	v_exp_f32_e64 v213, -|v208|
	v_exp_f32_e64 v214, -|v207|
	v_exp_f32_e64 v215, -|v206|
	v_max_f32_e32 v216, 0, v208
	v_max_f32_e32 v217, 0, v207
	v_max_f32_e32 v218, 0, v206
	v_add_f32_e32 v213, 1.0, v213
	v_add_f32_e32 v214, 1.0, v214
	v_add_f32_e32 v215, 1.0, v215
	v_log_f32_e32 v213, v213
	v_log_f32_e32 v214, v214
	v_log_f32_e32 v215, v215
	v_cmp_lt_i32_e32 vcc, 28, v212
	v_cmp_lt_i32_e64 s[92:93], 27, v212
	v_cmp_lt_i32_e64 s[94:95], 26, v212
	v_add_f32_e32 v213, v216, v213
	v_add_f32_e32 v214, v217, v214
	v_add_f32_e32 v215, v218, v215
	v_cndmask_b32_e64 v213, 0, -v213, vcc
	v_cndmask_b32_e64 v214, 0, -v214, s[92:93]
	v_cndmask_b32_e64 v215, 0, -v215, s[94:95]
	v_add_f32_e32 v146, v146, v213
	v_add_f32_e32 v208, v208, v146
	v_add_f32_e32 v146, v146, v214
	v_add_f32_e32 v207, v207, v146
	v_add_f32_e32 v146, v146, v215
	v_add_f32_e32 v206, v206, v146
	s_waitcnt lgkmcnt(5)
; template <int DH, int MODE>
; __device__ void attn_item(const Params& p, int layer, int b, int blk, int head, char* smem) {
;     ...
;         const int qpos = blk * 128 + row;
;         const int kpb = ktok + half * 32;
;         float run = 0.f;
; #pragma unroll 2
;         for (int c = 7; c >= 0; --c) {
;           float4 v = s4[c];
;           float e[4] = {v.x, v.y, v.z, v.w};
; #pragma unroll
;           for (int k = 3; k >= 0; --k) {
;             float z = e[k];
;             bool valid = (kpb + c * 4 + k) < qpos;
;             float sp = fmaxf(z, 0.f) + __builtin_amdgcn_logf(1.f + __builtin_amdgcn_exp2f(-fabsf(z)));
;             run += valid ? -sp : 0.f;
;             e[k] = z + run;
;           }
;           s4[c] = make_float4(e[0], e[1], e[2], e[3]);
;         }
	v_exp_f32_e64 v213, -|v205|
	v_exp_f32_e64 v214, -|v204|
	v_exp_f32_e64 v215, -|v203|
	v_max_f32_e32 v216, 0, v205
	v_max_f32_e32 v217, 0, v204
	v_max_f32_e32 v218, 0, v203
	v_add_f32_e32 v213, 1.0, v213
	v_add_f32_e32 v214, 1.0, v214
	v_add_f32_e32 v215, 1.0, v215
	v_log_f32_e32 v213, v213
	v_log_f32_e32 v214, v214
	v_log_f32_e32 v215, v215
	v_cmp_lt_i32_e32 vcc, 25, v212
	v_cmp_lt_i32_e64 s[92:93], 24, v212
	v_cmp_lt_i32_e64 s[94:95], 23, v212
	v_add_f32_e32 v213, v216, v213
	v_add_f32_e32 v214, v217, v214
	v_add_f32_e32 v215, v218, v215
	v_cndmask_b32_e64 v213, 0, -v213, vcc
	v_cndmask_b32_e64 v214, 0, -v214, s[92:93]
	v_cndmask_b32_e64 v215, 0, -v215, s[94:95]
	v_add_f32_e32 v146, v146, v213
	v_add_f32_e32 v205, v205, v146
	v_add_f32_e32 v146, v146, v214
	v_add_f32_e32 v204, v204, v146
	v_add_f32_e32 v146, v146, v215
	v_add_f32_e32 v203, v203, v146
	v_exp_f32_e64 v213, -|v202|
	v_exp_f32_e64 v214, -|v201|
	v_exp_f32_e64 v215, -|v200|
	v_max_f32_e32 v216, 0, v202
	v_max_f32_e32 v217, 0, v201
	v_max_f32_e32 v218, 0, v200
	v_add_f32_e32 v213, 1.0, v213
	v_add_f32_e32 v214, 1.0, v214
	v_add_f32_e32 v215, 1.0, v215
	v_log_f32_e32 v213, v213
	v_log_f32_e32 v214, v214
	v_log_f32_e32 v215, v215
	v_cmp_lt_i32_e32 vcc, 22, v212
	v_cmp_lt_i32_e64 s[92:93], 21, v212
	v_cmp_lt_i32_e64 s[94:95], 20, v212
	v_add_f32_e32 v213, v216, v213
	v_add_f32_e32 v214, v217, v214
	v_add_f32_e32 v215, v218, v215
	v_cndmask_b32_e64 v213, 0, -v213, vcc
	v_cndmask_b32_e64 v214, 0, -v214, s[92:93]
	v_cndmask_b32_e64 v215, 0, -v215, s[94:95]
	v_add_f32_e32 v146, v146, v213
	v_add_f32_e32 v202, v202, v146
	v_add_f32_e32 v146, v146, v214
	v_add_f32_e32 v201, v201, v146
	v_add_f32_e32 v146, v146, v215
	v_add_f32_e32 v200, v200, v146
	s_waitcnt lgkmcnt(4)
	v_exp_f32_e64 v213, -|v199|
	v_exp_f32_e64 v214, -|v198|
	v_exp_f32_e64 v215, -|v197|
	v_max_f32_e32 v216, 0, v199
	v_max_f32_e32 v217, 0, v198
	v_max_f32_e32 v218, 0, v197
	v_add_f32_e32 v213, 1.0, v213
	v_add_f32_e32 v214, 1.0, v214
	v_add_f32_e32 v215, 1.0, v215
	v_log_f32_e32 v213, v213
	v_log_f32_e32 v214, v214
	v_log_f32_e32 v215, v215
	v_cmp_lt_i32_e32 vcc, 19, v212
	v_cmp_lt_i32_e64 s[92:93], 18, v212
	v_cmp_lt_i32_e64 s[94:95], 17, v212
	v_add_f32_e32 v213, v216, v213
	v_add_f32_e32 v214, v217, v214
	v_add_f32_e32 v215, v218, v215
	v_cndmask_b32_e64 v213, 0, -v213, vcc
	v_cndmask_b32_e64 v214, 0, -v214, s[92:93]
	v_cndmask_b32_e64 v215, 0, -v215, s[94:95]
	v_add_f32_e32 v146, v146, v213
	v_add_f32_e32 v199, v199, v146
	v_add_f32_e32 v146, v146, v214
	v_add_f32_e32 v198, v198, v146
	v_add_f32_e32 v146, v146, v215
	v_add_f32_e32 v197, v197, v146
	s_waitcnt lgkmcnt(3)
	v_exp_f32_e64 v213, -|v196|
	v_exp_f32_e64 v214, -|v195|
	v_exp_f32_e64 v215, -|v194|
	v_max_f32_e32 v216, 0, v196
	v_max_f32_e32 v217, 0, v195
	v_max_f32_e32 v218, 0, v194
	v_add_f32_e32 v213, 1.0, v213
	v_add_f32_e32 v214, 1.0, v214
	v_add_f32_e32 v215, 1.0, v215
	v_log_f32_e32 v213, v213
	v_log_f32_e32 v214, v214
	v_log_f32_e32 v215, v215
	v_cmp_lt_i32_e32 vcc, 16, v212
	v_cmp_lt_i32_e64 s[92:93], 15, v212
	v_cmp_lt_i32_e64 s[94:95], 14, v212
	v_add_f32_e32 v213, v216, v213
	v_add_f32_e32 v214, v217, v214
	v_add_f32_e32 v215, v218, v215
	v_cndmask_b32_e64 v213, 0, -v213, vcc
	v_cndmask_b32_e64 v214, 0, -v214, s[92:93]
	v_cndmask_b32_e64 v215, 0, -v215, s[94:95]
	v_add_f32_e32 v146, v146, v213
	v_add_f32_e32 v196, v196, v146
	v_add_f32_e32 v146, v146, v214
	v_add_f32_e32 v195, v195, v146
	v_add_f32_e32 v146, v146, v215
	v_add_f32_e32 v194, v194, v146
	s_waitcnt lgkmcnt(2)
; template <int DH, int MODE>
; __device__ void attn_item(const Params& p, int layer, int b, int blk, int head, char* smem) {
;     ...
;         const int qpos = blk * 128 + row;
;         const int kpb = ktok + half * 32;
;         float run = 0.f;
; #pragma unroll 2
;         for (int c = 7; c >= 0; --c) {
;           float4 v = s4[c];
;           float e[4] = {v.x, v.y, v.z, v.w};
; #pragma unroll
;           for (int k = 3; k >= 0; --k) {
;             float z = e[k];
;             bool valid = (kpb + c * 4 + k) < qpos;
;             float sp = fmaxf(z, 0.f) + __builtin_amdgcn_logf(1.f + __builtin_amdgcn_exp2f(-fabsf(z)));
;             run += valid ? -sp : 0.f;
;             e[k] = z + run;
;           }
;           s4[c] = make_float4(e[0], e[1], e[2], e[3]);
;         }
	v_exp_f32_e64 v213, -|v193|
	v_exp_f32_e64 v214, -|v192|
	v_exp_f32_e64 v215, -|v191|
	v_max_f32_e32 v216, 0, v193
	v_max_f32_e32 v217, 0, v192
	v_max_f32_e32 v218, 0, v191
	v_add_f32_e32 v213, 1.0, v213
	v_add_f32_e32 v214, 1.0, v214
	v_add_f32_e32 v215, 1.0, v215
	v_log_f32_e32 v213, v213
	v_log_f32_e32 v214, v214
	v_log_f32_e32 v215, v215
	v_cmp_lt_i32_e32 vcc, 13, v212
	v_cmp_lt_i32_e64 s[92:93], 12, v212
	v_cmp_lt_i32_e64 s[94:95], 11, v212
	v_add_f32_e32 v213, v216, v213
	v_add_f32_e32 v214, v217, v214
	v_add_f32_e32 v215, v218, v215
	v_cndmask_b32_e64 v213, 0, -v213, vcc
	v_cndmask_b32_e64 v214, 0, -v214, s[92:93]
	v_cndmask_b32_e64 v215, 0, -v215, s[94:95]
	v_add_f32_e32 v146, v146, v213
	v_add_f32_e32 v193, v193, v146
	v_add_f32_e32 v146, v146, v214
	v_add_f32_e32 v192, v192, v146
	v_add_f32_e32 v146, v146, v215
	v_add_f32_e32 v191, v191, v146
	v_exp_f32_e64 v213, -|v190|
	v_exp_f32_e64 v214, -|v189|
	v_exp_f32_e64 v215, -|v188|
	v_max_f32_e32 v216, 0, v190
	v_max_f32_e32 v217, 0, v189
	v_max_f32_e32 v218, 0, v188
	v_add_f32_e32 v213, 1.0, v213
	v_add_f32_e32 v214, 1.0, v214
	v_add_f32_e32 v215, 1.0, v215
	v_log_f32_e32 v213, v213
	v_log_f32_e32 v214, v214
	v_log_f32_e32 v215, v215
	v_cmp_lt_i32_e32 vcc, 10, v212
	v_cmp_lt_i32_e64 s[92:93], 9, v212
	v_cmp_lt_i32_e64 s[94:95], 8, v212
	v_add_f32_e32 v213, v216, v213
	v_add_f32_e32 v214, v217, v214
	v_add_f32_e32 v215, v218, v215
	v_cndmask_b32_e64 v213, 0, -v213, vcc
	v_cndmask_b32_e64 v214, 0, -v214, s[92:93]
	v_cndmask_b32_e64 v215, 0, -v215, s[94:95]
	v_add_f32_e32 v146, v146, v213
	v_add_f32_e32 v190, v190, v146
	v_add_f32_e32 v146, v146, v214
	v_add_f32_e32 v189, v189, v146
	v_add_f32_e32 v146, v146, v215
	v_add_f32_e32 v188, v188, v146
	s_waitcnt lgkmcnt(1)
	v_exp_f32_e64 v213, -|v187|
	v_exp_f32_e64 v214, -|v186|
	v_exp_f32_e64 v215, -|v185|
	v_max_f32_e32 v216, 0, v187
	v_max_f32_e32 v217, 0, v186
	v_max_f32_e32 v218, 0, v185
	v_add_f32_e32 v213, 1.0, v213
	v_add_f32_e32 v214, 1.0, v214
	v_add_f32_e32 v215, 1.0, v215
	v_log_f32_e32 v213, v213
	v_log_f32_e32 v214, v214
	v_log_f32_e32 v215, v215
	v_cmp_lt_i32_e32 vcc, 7, v212
	v_cmp_lt_i32_e64 s[92:93], 6, v212
	v_cmp_lt_i32_e64 s[94:95], 5, v212
	v_add_f32_e32 v213, v216, v213
	v_add_f32_e32 v214, v217, v214
	v_add_f32_e32 v215, v218, v215
	v_cndmask_b32_e64 v213, 0, -v213, vcc
	v_cndmask_b32_e64 v214, 0, -v214, s[92:93]
	v_cndmask_b32_e64 v215, 0, -v215, s[94:95]
	v_add_f32_e32 v146, v146, v213
	v_add_f32_e32 v187, v187, v146
	v_add_f32_e32 v146, v146, v214
	v_add_f32_e32 v186, v186, v146
	v_add_f32_e32 v146, v146, v215
	v_add_f32_e32 v185, v185, v146
	s_waitcnt lgkmcnt(0)
	v_exp_f32_e64 v213, -|v184|
	v_exp_f32_e64 v214, -|v183|
	v_exp_f32_e64 v215, -|v182|
	v_max_f32_e32 v216, 0, v184
	v_max_f32_e32 v217, 0, v183
	v_max_f32_e32 v218, 0, v182
	v_add_f32_e32 v213, 1.0, v213
	v_add_f32_e32 v214, 1.0, v214
	v_add_f32_e32 v215, 1.0, v215
	v_log_f32_e32 v213, v213
	v_log_f32_e32 v214, v214
	v_log_f32_e32 v215, v215
	v_cmp_lt_i32_e32 vcc, 4, v212
	v_cmp_lt_i32_e64 s[92:93], 3, v212
	v_cmp_lt_i32_e64 s[94:95], 2, v212
	v_add_f32_e32 v213, v216, v213
	v_add_f32_e32 v214, v217, v214
	v_add_f32_e32 v215, v218, v215
	v_cndmask_b32_e64 v213, 0, -v213, vcc
	v_cndmask_b32_e64 v214, 0, -v214, s[92:93]
	v_cndmask_b32_e64 v215, 0, -v215, s[94:95]
	v_add_f32_e32 v146, v146, v213
	v_add_f32_e32 v184, v184, v146
	v_add_f32_e32 v146, v146, v214
	v_add_f32_e32 v183, v183, v146
	v_add_f32_e32 v146, v146, v215
	v_add_f32_e32 v182, v182, v146
	v_exp_f32_e64 v213, -|v181|
	v_exp_f32_e64 v214, -|v180|
	v_max_f32_e32 v216, 0, v181
	v_max_f32_e32 v217, 0, v180
	v_add_f32_e32 v213, 1.0, v213
	v_add_f32_e32 v214, 1.0, v214
	v_log_f32_e32 v213, v213
	v_log_f32_e32 v214, v214
	v_cmp_lt_i32_e32 vcc, 1, v212
	v_cmp_lt_i32_e64 s[92:93], 0, v212
	s_nop 0
	v_add_f32_e32 v213, v216, v213
	v_add_f32_e32 v214, v217, v214
	v_cndmask_b32_e64 v213, 0, -v213, vcc
	v_cndmask_b32_e64 v214, 0, -v214, s[92:93]
	v_add_f32_e32 v146, v146, v213
	v_add_f32_e32 v181, v181, v146
	v_add_f32_e32 v146, v146, v214
	v_add_f32_e32 v180, v180, v146
	s_branch .Lsb_p1done_1

; template <int DH, int MODE>
; __device__ void attn_item(const Params& p, int layer, int b, int blk, int head, char* smem) {
;     ...
;         const int qpos = blk * 128 + row;
;         const int kpb = ktok + half * 32;
;         float run = 0.f;
; #pragma unroll 2
;         for (int c = 7; c >= 0; --c) {
;           float4 v = s4[c];
;           float e[4] = {v.x, v.y, v.z, v.w};
; #pragma unroll
;           for (int k = 3; k >= 0; --k) {
;             float z = e[k];
;             bool valid = (kpb + c * 4 + k) < qpos;
;             float sp = fmaxf(z, 0.f) + __builtin_amdgcn_logf(1.f + __builtin_amdgcn_exp2f(-fabsf(z)));
;             run += valid ? -sp : 0.f;
;             e[k] = z + run;
;           }
;           s4[c] = make_float4(e[0], e[1], e[2], e[3]);
;         }
.LBB0_1166:
	s_or_b64 exec, exec, s[44:45]
	s_add_i32 s16, s80, 1
	s_min_i32 s44, s16, s78
	s_sub_i32 s44, s78, s44
	s_lshl_b32 s44, s44, 6
	s_ashr_i32 s45, s44, 31
	s_add_u32 s44, s44, s77
	s_addc_u32 s45, s45, 0
	s_waitcnt lgkmcnt(0)
	s_barrier
	ds_write_b16 v171, v96
	ds_write_b16_d16_hi v171, v96 offset:64
	ds_write_b16 v171, v97 offset:128
	ds_write_b16_d16_hi v171, v97 offset:192
	ds_write_b16 v171, v98 offset:256
	ds_write_b16_d16_hi v171, v98 offset:320
	ds_write_b16 v171, v99 offset:384
	ds_write_b16_d16_hi v171, v99 offset:448
	ds_write_b16 v171, v100 offset:2048
	ds_write_b16_d16_hi v171, v100 offset:2112
	ds_write_b16 v171, v101 offset:2176
	ds_write_b16_d16_hi v171, v101 offset:2240
	ds_write_b16 v171, v102 offset:2304
	ds_write_b16_d16_hi v171, v102 offset:2368
	ds_write_b16 v171, v103 offset:2432
	ds_write_b16_d16_hi v171, v103 offset:2496
	s_waitcnt vmcnt(1)
	ds_write_b16 v171, v108 offset:4096
	ds_write_b16_d16_hi v171, v108 offset:4160
	ds_write_b16 v171, v109 offset:4224
	ds_write_b16_d16_hi v171, v109 offset:4288
	ds_write_b16 v171, v110 offset:4352
	ds_write_b16_d16_hi v171, v110 offset:4416
	ds_write_b16 v171, v111 offset:4480
	ds_write_b16_d16_hi v171, v111 offset:4544
	s_waitcnt vmcnt(0)
	ds_write_b16 v171, v104 offset:6144
	ds_write_b16_d16_hi v171, v104 offset:6208
	ds_write_b16 v171, v105 offset:6272
	ds_write_b16_d16_hi v171, v105 offset:6336
	ds_write_b16 v171, v106 offset:6400
	ds_write_b16_d16_hi v171, v106 offset:6464
	ds_write_b16 v171, v107 offset:6528
	ds_write_b16_d16_hi v171, v107 offset:6592
	v_lshl_add_u64 v[96:97], s[44:45], 0, v[134:135]
	v_mad_u64_u32 v[104:105], s[46:47], v96, s39, v[140:141]
	v_or_b32_e32 v96, s44, v132
	v_mad_i32_i24 v105, v97, s39, v105
	v_mad_u64_u32 v[106:107], s[46:47], v96, s39, v[142:143]
	v_add_co_u32_e32 v96, vcc, s64, v104
	v_mad_i32_i24 v107, s45, v160, v107
	s_nop 0
	v_addc_co_u32_e32 v97, vcc, 0, v105, vcc
	v_add_co_u32_e32 v98, vcc, 0x4c000, v104
	s_nop 1
	v_addc_co_u32_e32 v99, vcc, 0, v105, vcc
	v_add_co_u32_e32 v100, vcc, 0x72000, v104
	global_load_dwordx4 v[120:123], v[96:97], off
	global_load_dwordx4 v[116:119], v[98:99], off
	v_addc_co_u32_e32 v101, vcc, 0, v105, vcc
	global_load_dwordx4 v[96:99], v[106:107], off
	global_load_dwordx4 v[124:127], v[100:101], off
	s_nop 0
	global_load_dwordx4 v[100:103], v[106:107], off offset:64
	global_load_dwordx4 v[108:111], v[106:107], off offset:128
	global_load_dwordx4 v[112:115], v[104:105], off
	s_nop 0
	global_load_dwordx4 v[104:107], v[106:107], off offset:192
	s_and_saveexec_b64 s[44:45], s[10:11]
	s_cbranch_execz .LBB0_1177
	v_mov_b32_e32 v146, 0
	s_mov_b32 s46, 0
	v_mov_b32_e32 v148, v166
	s_setprio 1
	ds_read_b128 v[208:211], v167 offset:112
	ds_read_b128 v[204:207], v167 offset:96
	ds_read_b128 v[200:203], v167 offset:80
	ds_read_b128 v[196:199], v167 offset:64
	ds_read_b128 v[192:195], v167 offset:48
	ds_read_b128 v[188:191], v167 offset:32
	ds_read_b128 v[184:187], v167 offset:16
	ds_read_b128 v[180:183], v167
	v_sub_u32_e32 v212, v144, v173
	v_add_u32_e32 v212, 0xffffc040, v212
	v_cmp_lt_i32_e32 vcc, 31, v212
	s_cmp_eq_u64 vcc, exec
	s_cbranch_scc1 .Lsb_p1fast_0
	s_waitcnt lgkmcnt(7)
	v_exp_f32_e64 v213, -|v211|
	v_exp_f32_e64 v214, -|v210|
	v_exp_f32_e64 v215, -|v209|
	v_max_f32_e32 v216, 0, v211
	v_max_f32_e32 v217, 0, v210
	v_max_f32_e32 v218, 0, v209
	v_add_f32_e32 v213, 1.0, v213
	v_add_f32_e32 v214, 1.0, v214
	v_add_f32_e32 v215, 1.0, v215
	v_log_f32_e32 v213, v213
	v_log_f32_e32 v214, v214
	v_log_f32_e32 v215, v215
	v_cmp_lt_i32_e32 vcc, 31, v212
	v_cmp_lt_i32_e64 s[92:93], 30, v212
	v_cmp_lt_i32_e64 s[94:95], 29, v212
	v_add_f32_e32 v213, v216, v213
	v_add_f32_e32 v214, v217, v214
	v_add_f32_e32 v215, v218, v215
	v_cndmask_b32_e64 v213, 0, -v213, vcc
	v_cndmask_b32_e64 v214, 0, -v214, s[92:93]
	v_cndmask_b32_e64 v215, 0, -v215, s[94:95]
	v_add_f32_e32 v146, v146, v213
	v_add_f32_e32 v211, v211, v146
	v_add_f32_e32 v146, v146, v214
	v_add_f32_e32 v210, v210, v146
	v_add_f32_e32 v146, v146, v215
	v_add_f32_e32 v209, v209, v146
	s_waitcnt lgkmcnt(6)
	v_exp_f32_e64 v213, -|v208|
	v_exp_f32_e64 v214, -|v207|
	v_exp_f32_e64 v215, -|v206|
	v_max_f32_e32 v216, 0, v208
	v_max_f32_e32 v217, 0, v207
	v_max_f32_e32 v218, 0, v206
	v_add_f32_e32 v213, 1.0, v213
	v_add_f32_e32 v214, 1.0, v214
	v_add_f32_e32 v215, 1.0, v215
	v_log_f32_e32 v213, v213
	v_log_f32_e32 v214, v214
	v_log_f32_e32 v215, v215
	v_cmp_lt_i32_e32 vcc, 28, v212
	v_cmp_lt_i32_e64 s[92:93], 27, v212
	v_cmp_lt_i32_e64 s[94:95], 26, v212
	v_add_f32_e32 v213, v216, v213
	v_add_f32_e32 v214, v217, v214
	v_add_f32_e32 v215, v218, v215
	v_cndmask_b32_e64 v213, 0, -v213, vcc
	v_cndmask_b32_e64 v214, 0, -v214, s[92:93]
	v_cndmask_b32_e64 v215, 0, -v215, s[94:95]
	v_add_f32_e32 v146, v146, v213
	v_add_f32_e32 v208, v208, v146
	v_add_f32_e32 v146, v146, v214
	v_add_f32_e32 v207, v207, v146
	v_add_f32_e32 v146, v146, v215
	v_add_f32_e32 v206, v206, v146
	s_waitcnt lgkmcnt(5)
; template <int DH, int MODE>
; __device__ void attn_item(const Params& p, int layer, int b, int blk, int head, char* smem) {
;     ...
;         const int qpos = blk * 128 + row;
;         const int kpb = ktok + half * 32;
;         float run = 0.f;
; #pragma unroll 2
;         for (int c = 7; c >= 0; --c) {
;           float4 v = s4[c];
;           float e[4] = {v.x, v.y, v.z, v.w};
; #pragma unroll
;           for (int k = 3; k >= 0; --k) {
;             float z = e[k];
;             bool valid = (kpb + c * 4 + k) < qpos;
;             float sp = fmaxf(z, 0.f) + __builtin_amdgcn_logf(1.f + __builtin_amdgcn_exp2f(-fabsf(z)));
;             run += valid ? -sp : 0.f;
;             e[k] = z + run;
;           }
;           s4[c] = make_float4(e[0], e[1], e[2], e[3]);
;         }
	v_exp_f32_e64 v213, -|v205|
	v_exp_f32_e64 v214, -|v204|
	v_exp_f32_e64 v215, -|v203|
	v_max_f32_e32 v216, 0, v205
	v_max_f32_e32 v217, 0, v204
	v_max_f32_e32 v218, 0, v203
	v_add_f32_e32 v213, 1.0, v213
	v_add_f32_e32 v214, 1.0, v214
	v_add_f32_e32 v215, 1.0, v215
	v_log_f32_e32 v213, v213
	v_log_f32_e32 v214, v214
	v_log_f32_e32 v215, v215
	v_cmp_lt_i32_e32 vcc, 25, v212
	v_cmp_lt_i32_e64 s[92:93], 24, v212
	v_cmp_lt_i32_e64 s[94:95], 23, v212
	v_add_f32_e32 v213, v216, v213
	v_add_f32_e32 v214, v217, v214
	v_add_f32_e32 v215, v218, v215
	v_cndmask_b32_e64 v213, 0, -v213, vcc
	v_cndmask_b32_e64 v214, 0, -v214, s[92:93]
	v_cndmask_b32_e64 v215, 0, -v215, s[94:95]
	v_add_f32_e32 v146, v146, v213
	v_add_f32_e32 v205, v205, v146
	v_add_f32_e32 v146, v146, v214
	v_add_f32_e32 v204, v204, v146
	v_add_f32_e32 v146, v146, v215
	v_add_f32_e32 v203, v203, v146
	v_exp_f32_e64 v213, -|v202|
	v_exp_f32_e64 v214, -|v201|
	v_exp_f32_e64 v215, -|v200|
	v_max_f32_e32 v216, 0, v202
	v_max_f32_e32 v217, 0, v201
	v_max_f32_e32 v218, 0, v200
	v_add_f32_e32 v213, 1.0, v213
	v_add_f32_e32 v214, 1.0, v214
	v_add_f32_e32 v215, 1.0, v215
	v_log_f32_e32 v213, v213
	v_log_f32_e32 v214, v214
	v_log_f32_e32 v215, v215
	v_cmp_lt_i32_e32 vcc, 22, v212
	v_cmp_lt_i32_e64 s[92:93], 21, v212
	v_cmp_lt_i32_e64 s[94:95], 20, v212
	v_add_f32_e32 v213, v216, v213
	v_add_f32_e32 v214, v217, v214
	v_add_f32_e32 v215, v218, v215
	v_cndmask_b32_e64 v213, 0, -v213, vcc
	v_cndmask_b32_e64 v214, 0, -v214, s[92:93]
	v_cndmask_b32_e64 v215, 0, -v215, s[94:95]
	v_add_f32_e32 v146, v146, v213
	v_add_f32_e32 v202, v202, v146
	v_add_f32_e32 v146, v146, v214
	v_add_f32_e32 v201, v201, v146
	v_add_f32_e32 v146, v146, v215
	v_add_f32_e32 v200, v200, v146
	s_waitcnt lgkmcnt(4)
	v_exp_f32_e64 v213, -|v199|
	v_exp_f32_e64 v214, -|v198|
	v_exp_f32_e64 v215, -|v197|
	v_max_f32_e32 v216, 0, v199
	v_max_f32_e32 v217, 0, v198
	v_max_f32_e32 v218, 0, v197
	v_add_f32_e32 v213, 1.0, v213
	v_add_f32_e32 v214, 1.0, v214
	v_add_f32_e32 v215, 1.0, v215
	v_log_f32_e32 v213, v213
	v_log_f32_e32 v214, v214
	v_log_f32_e32 v215, v215
	v_cmp_lt_i32_e32 vcc, 19, v212
	v_cmp_lt_i32_e64 s[92:93], 18, v212
	v_cmp_lt_i32_e64 s[94:95], 17, v212
	v_add_f32_e32 v213, v216, v213
	v_add_f32_e32 v214, v217, v214
	v_add_f32_e32 v215, v218, v215
	v_cndmask_b32_e64 v213, 0, -v213, vcc
	v_cndmask_b32_e64 v214, 0, -v214, s[92:93]
	v_cndmask_b32_e64 v215, 0, -v215, s[94:95]
	v_add_f32_e32 v146, v146, v213
	v_add_f32_e32 v199, v199, v146
	v_add_f32_e32 v146, v146, v214
	v_add_f32_e32 v198, v198, v146
	v_add_f32_e32 v146, v146, v215
	v_add_f32_e32 v197, v197, v146
	s_waitcnt lgkmcnt(3)
	v_exp_f32_e64 v213, -|v196|
	v_exp_f32_e64 v214, -|v195|
	v_exp_f32_e64 v215, -|v194|
	v_max_f32_e32 v216, 0, v196
	v_max_f32_e32 v217, 0, v195
	v_max_f32_e32 v218, 0, v194
	v_add_f32_e32 v213, 1.0, v213
	v_add_f32_e32 v214, 1.0, v214
	v_add_f32_e32 v215, 1.0, v215
	v_log_f32_e32 v213, v213
	v_log_f32_e32 v214, v214
	v_log_f32_e32 v215, v215
	v_cmp_lt_i32_e32 vcc, 16, v212
	v_cmp_lt_i32_e64 s[92:93], 15, v212
	v_cmp_lt_i32_e64 s[94:95], 14, v212
	v_add_f32_e32 v213, v216, v213
	v_add_f32_e32 v214, v217, v214
	v_add_f32_e32 v215, v218, v215
	v_cndmask_b32_e64 v213, 0, -v213, vcc
	v_cndmask_b32_e64 v214, 0, -v214, s[92:93]
	v_cndmask_b32_e64 v215, 0, -v215, s[94:95]
	v_add_f32_e32 v146, v146, v213
	v_add_f32_e32 v196, v196, v146
	v_add_f32_e32 v146, v146, v214
	v_add_f32_e32 v195, v195, v146
	v_add_f32_e32 v146, v146, v215
	v_add_f32_e32 v194, v194, v146
	s_waitcnt lgkmcnt(2)
; template <int DH, int MODE>
; __device__ void attn_item(const Params& p, int layer, int b, int blk, int head, char* smem) {
;     ...
;         const int qpos = blk * 128 + row;
;         const int kpb = ktok + half * 32;
;         float run = 0.f;
; #pragma unroll 2
;         for (int c = 7; c >= 0; --c) {
;           float4 v = s4[c];
;           float e[4] = {v.x, v.y, v.z, v.w};
; #pragma unroll
;           for (int k = 3; k >= 0; --k) {
;             float z = e[k];
;             bool valid = (kpb + c * 4 + k) < qpos;
;             float sp = fmaxf(z, 0.f) + __builtin_amdgcn_logf(1.f + __builtin_amdgcn_exp2f(-fabsf(z)));
;             run += valid ? -sp : 0.f;
;             e[k] = z + run;
;           }
;           s4[c] = make_float4(e[0], e[1], e[2], e[3]);
;         }
	v_exp_f32_e64 v213, -|v193|
	v_exp_f32_e64 v214, -|v192|
	v_exp_f32_e64 v215, -|v191|
	v_max_f32_e32 v216, 0, v193
	v_max_f32_e32 v217, 0, v192
	v_max_f32_e32 v218, 0, v191
	v_add_f32_e32 v213, 1.0, v213
	v_add_f32_e32 v214, 1.0, v214
	v_add_f32_e32 v215, 1.0, v215
	v_log_f32_e32 v213, v213
	v_log_f32_e32 v214, v214
	v_log_f32_e32 v215, v215
	v_cmp_lt_i32_e32 vcc, 13, v212
	v_cmp_lt_i32_e64 s[92:93], 12, v212
	v_cmp_lt_i32_e64 s[94:95], 11, v212
	v_add_f32_e32 v213, v216, v213
	v_add_f32_e32 v214, v217, v214
	v_add_f32_e32 v215, v218, v215
	v_cndmask_b32_e64 v213, 0, -v213, vcc
	v_cndmask_b32_e64 v214, 0, -v214, s[92:93]
	v_cndmask_b32_e64 v215, 0, -v215, s[94:95]
	v_add_f32_e32 v146, v146, v213
	v_add_f32_e32 v193, v193, v146
	v_add_f32_e32 v146, v146, v214
	v_add_f32_e32 v192, v192, v146
	v_add_f32_e32 v146, v146, v215
	v_add_f32_e32 v191, v191, v146
	v_exp_f32_e64 v213, -|v190|
	v_exp_f32_e64 v214, -|v189|
	v_exp_f32_e64 v215, -|v188|
	v_max_f32_e32 v216, 0, v190
	v_max_f32_e32 v217, 0, v189
	v_max_f32_e32 v218, 0, v188
	v_add_f32_e32 v213, 1.0, v213
	v_add_f32_e32 v214, 1.0, v214
	v_add_f32_e32 v215, 1.0, v215
	v_log_f32_e32 v213, v213
	v_log_f32_e32 v214, v214
	v_log_f32_e32 v215, v215
	v_cmp_lt_i32_e32 vcc, 10, v212
	v_cmp_lt_i32_e64 s[92:93], 9, v212
	v_cmp_lt_i32_e64 s[94:95], 8, v212
	v_add_f32_e32 v213, v216, v213
	v_add_f32_e32 v214, v217, v214
	v_add_f32_e32 v215, v218, v215
	v_cndmask_b32_e64 v213, 0, -v213, vcc
	v_cndmask_b32_e64 v214, 0, -v214, s[92:93]
	v_cndmask_b32_e64 v215, 0, -v215, s[94:95]
	v_add_f32_e32 v146, v146, v213
	v_add_f32_e32 v190, v190, v146
	v_add_f32_e32 v146, v146, v214
	v_add_f32_e32 v189, v189, v146
	v_add_f32_e32 v146, v146, v215
	v_add_f32_e32 v188, v188, v146
	s_waitcnt lgkmcnt(1)
	v_exp_f32_e64 v213, -|v187|
	v_exp_f32_e64 v214, -|v186|
	v_exp_f32_e64 v215, -|v185|
	v_max_f32_e32 v216, 0, v187
	v_max_f32_e32 v217, 0, v186
	v_max_f32_e32 v218, 0, v185
	v_add_f32_e32 v213, 1.0, v213
	v_add_f32_e32 v214, 1.0, v214
	v_add_f32_e32 v215, 1.0, v215
	v_log_f32_e32 v213, v213
	v_log_f32_e32 v214, v214
	v_log_f32_e32 v215, v215
	v_cmp_lt_i32_e32 vcc, 7, v212
	v_cmp_lt_i32_e64 s[92:93], 6, v212
	v_cmp_lt_i32_e64 s[94:95], 5, v212
	v_add_f32_e32 v213, v216, v213
	v_add_f32_e32 v214, v217, v214
	v_add_f32_e32 v215, v218, v215
	v_cndmask_b32_e64 v213, 0, -v213, vcc
	v_cndmask_b32_e64 v214, 0, -v214, s[92:93]
	v_cndmask_b32_e64 v215, 0, -v215, s[94:95]
	v_add_f32_e32 v146, v146, v213
	v_add_f32_e32 v187, v187, v146
	v_add_f32_e32 v146, v146, v214
	v_add_f32_e32 v186, v186, v146
	v_add_f32_e32 v146, v146, v215
	v_add_f32_e32 v185, v185, v146
	s_waitcnt lgkmcnt(0)
	v_exp_f32_e64 v213, -|v184|
	v_exp_f32_e64 v214, -|v183|
	v_exp_f32_e64 v215, -|v182|
	v_max_f32_e32 v216, 0, v184
	v_max_f32_e32 v217, 0, v183
	v_max_f32_e32 v218, 0, v182
	v_add_f32_e32 v213, 1.0, v213
	v_add_f32_e32 v214, 1.0, v214
	v_add_f32_e32 v215, 1.0, v215
	v_log_f32_e32 v213, v213
	v_log_f32_e32 v214, v214
	v_log_f32_e32 v215, v215
	v_cmp_lt_i32_e32 vcc, 4, v212
	v_cmp_lt_i32_e64 s[92:93], 3, v212
	v_cmp_lt_i32_e64 s[94:95], 2, v212
	v_add_f32_e32 v213, v216, v213
	v_add_f32_e32 v214, v217, v214
	v_add_f32_e32 v215, v218, v215
	v_cndmask_b32_e64 v213, 0, -v213, vcc
	v_cndmask_b32_e64 v214, 0, -v214, s[92:93]
	v_cndmask_b32_e64 v215, 0, -v215, s[94:95]
	v_add_f32_e32 v146, v146, v213
	v_add_f32_e32 v184, v184, v146
	v_add_f32_e32 v146, v146, v214
	v_add_f32_e32 v183, v183, v146
	v_add_f32_e32 v146, v146, v215
	v_add_f32_e32 v182, v182, v146
	v_exp_f32_e64 v213, -|v181|
	v_exp_f32_e64 v214, -|v180|
	v_max_f32_e32 v216, 0, v181
	v_max_f32_e32 v217, 0, v180
	v_add_f32_e32 v213, 1.0, v213
	v_add_f32_e32 v214, 1.0, v214
	v_log_f32_e32 v213, v213
	v_log_f32_e32 v214, v214
	v_cmp_lt_i32_e32 vcc, 1, v212
	v_cmp_lt_i32_e64 s[92:93], 0, v212
	s_nop 0
	v_add_f32_e32 v213, v216, v213
	v_add_f32_e32 v214, v217, v214
	v_cndmask_b32_e64 v213, 0, -v213, vcc
	v_cndmask_b32_e64 v214, 0, -v214, s[92:93]
	v_add_f32_e32 v146, v146, v213
	v_add_f32_e32 v181, v181, v146
	v_add_f32_e32 v146, v146, v214
	v_add_f32_e32 v180, v180, v146
	s_branch .Lsb_p1done_0

; __device__ __forceinline__ unsigned pack2(float a, float b) { return (unsigned)f2bf(a) | ((unsigned)f2bf(b) << 16); }
; template <int DH, int MODE>
; __device__ void attn_item(const Params& p, int layer, int b, int blk, int head, char* smem) {
;     ...
;         float other = __shfl_xor(run, 1);
;         float offs = m_run + (half == 0 ? other : 0.f);
; #pragma unroll 2
;         for (int s8 = 0; s8 < 4; ++s8) {
;           float4 va = s4[2 * s8], vb = s4[2 * s8 + 1];
;           float e[8] = {va.x, va.y, va.z, va.w, vb.x, vb.y, vb.z, vb.w};
;           float pv[8];
; #pragma unroll
;           for (int k = 0; k < 8; ++k) {
;             bool valid = (kpb + s8 * 8 + k) < qpos;
;             pv[k] = valid ? __builtin_amdgcn_exp2f(e[k] + offs) : 0.f;
;           }
;           uint4 ov;
;           ov.x = pack2(pv[0], pv[1]); ov.y = pack2(pv[2], pv[3]);
;           ov.z = pack2(pv[4], pv[5]); ov.w = pack2(pv[6], pv[7]);
;           *reinterpret_cast<uint4*>(prow + s8 * 16) = ov;
;         }
.Lsb_p1done_0:
	s_setprio 0
	ds_bpermute_b32 v147, v163, v146
	s_mov_b32 s81, 0
	v_mov_b32_e32 v175, v168
	v_mov_b32_e32 v177, v167
	s_waitcnt lgkmcnt(0)
	v_cndmask_b32_e64 v148, 0, v147, s[8:9]
	v_add_f32_e32 v176, v174, v148
	v_sub_u32_e32 v212, v144, v173
	v_add_u32_e32 v212, 0xffffc040, v212
	v_cmp_lt_i32_e32 vcc, 31, v212
	s_cmp_eq_u64 vcc, exec
	s_cbranch_scc1 .Lsb_p2fast_0
	v_add_f32_e32 v180, v176, v180
	v_add_f32_e32 v181, v176, v181
	v_add_f32_e32 v182, v176, v182
	v_exp_f32_e32 v180, v180
	v_exp_f32_e32 v181, v181
	v_exp_f32_e32 v182, v182
	v_cmp_lt_i32_e32 vcc, 0, v212
	v_cmp_lt_i32_e64 s[92:93], 1, v212
	v_cmp_lt_i32_e64 s[94:95], 2, v212
	v_cndmask_b32_e32 v180, 0, v180, vcc
	v_cndmask_b32_e64 v181, 0, v181, s[92:93]
	v_cndmask_b32_e64 v182, 0, v182, s[94:95]
	v_add_f32_e32 v183, v176, v183
	v_add_f32_e32 v184, v176, v184
	v_add_f32_e32 v185, v176, v185
	v_exp_f32_e32 v183, v183
	v_exp_f32_e32 v184, v184
	v_exp_f32_e32 v185, v185
	v_cmp_lt_i32_e32 vcc, 3, v212
	v_cmp_lt_i32_e64 s[92:93], 4, v212
	v_cmp_lt_i32_e64 s[94:95], 5, v212
	v_cndmask_b32_e32 v183, 0, v183, vcc
	v_cndmask_b32_e64 v184, 0, v184, s[92:93]
	v_cndmask_b32_e64 v185, 0, v185, s[94:95]
	v_add_f32_e32 v186, v176, v186
	v_add_f32_e32 v187, v176, v187
	v_add_f32_e32 v188, v176, v188
	v_exp_f32_e32 v186, v186
	v_exp_f32_e32 v187, v187
	v_exp_f32_e32 v188, v188
	v_cmp_lt_i32_e32 vcc, 6, v212
	v_cmp_lt_i32_e64 s[92:93], 7, v212
	v_cmp_lt_i32_e64 s[94:95], 8, v212
	v_cndmask_b32_e32 v186, 0, v186, vcc
	v_cndmask_b32_e64 v187, 0, v187, s[92:93]
	v_cndmask_b32_e64 v188, 0, v188, s[94:95]
	v_add_f32_e32 v189, v176, v189
	v_add_f32_e32 v190, v176, v190
	v_add_f32_e32 v191, v176, v191
	v_exp_f32_e32 v189, v189
	v_exp_f32_e32 v190, v190
	v_exp_f32_e32 v191, v191
	v_cmp_lt_i32_e32 vcc, 9, v212
	v_cmp_lt_i32_e64 s[92:93], 10, v212
	v_cmp_lt_i32_e64 s[94:95], 11, v212
	v_cndmask_b32_e32 v189, 0, v189, vcc
	v_cndmask_b32_e64 v190, 0, v190, s[92:93]
	v_cndmask_b32_e64 v191, 0, v191, s[94:95]
	v_add_f32_e32 v192, v176, v192
	v_add_f32_e32 v193, v176, v193
	v_add_f32_e32 v194, v176, v194
	v_exp_f32_e32 v192, v192
	v_exp_f32_e32 v193, v193
	v_exp_f32_e32 v194, v194
	v_cmp_lt_i32_e32 vcc, 12, v212
	v_cmp_lt_i32_e64 s[92:93], 13, v212
	v_cmp_lt_i32_e64 s[94:95], 14, v212
	v_cndmask_b32_e32 v192, 0, v192, vcc
	v_cndmask_b32_e64 v193, 0, v193, s[92:93]
	v_cndmask_b32_e64 v194, 0, v194, s[94:95]
	v_add_f32_e32 v195, v176, v195
	v_add_f32_e32 v196, v176, v196
	v_add_f32_e32 v197, v176, v197
	v_exp_f32_e32 v195, v195
	v_exp_f32_e32 v196, v196
	v_exp_f32_e32 v197, v197
	v_cmp_lt_i32_e32 vcc, 15, v212
	v_cmp_lt_i32_e64 s[92:93], 16, v212
	v_cmp_lt_i32_e64 s[94:95], 17, v212
	v_cndmask_b32_e32 v195, 0, v195, vcc
	v_cndmask_b32_e64 v196, 0, v196, s[92:93]
	v_cndmask_b32_e64 v197, 0, v197, s[94:95]
	v_add_f32_e32 v198, v176, v198
	v_add_f32_e32 v199, v176, v199
	v_add_f32_e32 v200, v176, v200
	v_exp_f32_e32 v198, v198
	v_exp_f32_e32 v199, v199
	v_exp_f32_e32 v200, v200
	v_cmp_lt_i32_e32 vcc, 18, v212
	v_cmp_lt_i32_e64 s[92:93], 19, v212
	v_cmp_lt_i32_e64 s[94:95], 20, v212
	v_cndmask_b32_e32 v198, 0, v198, vcc
	v_cndmask_b32_e64 v199, 0, v199, s[92:93]
	v_cndmask_b32_e64 v200, 0, v200, s[94:95]
	v_add_f32_e32 v201, v176, v201
	v_add_f32_e32 v202, v176, v202
	v_add_f32_e32 v203, v176, v203
	v_exp_f32_e32 v201, v201
	v_exp_f32_e32 v202, v202
	v_exp_f32_e32 v203, v203
	v_cmp_lt_i32_e32 vcc, 21, v212
	v_cmp_lt_i32_e64 s[92:93], 22, v212
	v_cmp_lt_i32_e64 s[94:95], 23, v212
	v_cndmask_b32_e32 v201, 0, v201, vcc
	v_cndmask_b32_e64 v202, 0, v202, s[92:93]
	v_cndmask_b32_e64 v203, 0, v203, s[94:95]
	v_add_f32_e32 v204, v176, v204
	v_add_f32_e32 v205, v176, v205
	v_add_f32_e32 v206, v176, v206
	v_exp_f32_e32 v204, v204
	v_exp_f32_e32 v205, v205
	v_exp_f32_e32 v206, v206
	v_cmp_lt_i32_e32 vcc, 24, v212
	v_cmp_lt_i32_e64 s[92:93], 25, v212
	v_cmp_lt_i32_e64 s[94:95], 26, v212
	v_cndmask_b32_e32 v204, 0, v204, vcc
	v_cndmask_b32_e64 v205, 0, v205, s[92:93]
	v_cndmask_b32_e64 v206, 0, v206, s[94:95]
	v_add_f32_e32 v207, v176, v207
	v_add_f32_e32 v208, v176, v208
	v_add_f32_e32 v209, v176, v209
	v_exp_f32_e32 v207, v207
	v_exp_f32_e32 v208, v208
	v_exp_f32_e32 v209, v209
	v_cmp_lt_i32_e32 vcc, 27, v212
	v_cmp_lt_i32_e64 s[92:93], 28, v212
	v_cmp_lt_i32_e64 s[94:95], 29, v212
	v_cndmask_b32_e32 v207, 0, v207, vcc
	v_cndmask_b32_e64 v208, 0, v208, s[92:93]
	v_cndmask_b32_e64 v209, 0, v209, s[94:95]
	v_add_f32_e32 v210, v176, v210
	v_add_f32_e32 v211, v176, v211
	v_exp_f32_e32 v210, v210
	v_exp_f32_e32 v211, v211
	v_cmp_lt_i32_e32 vcc, 30, v212
	v_cmp_lt_i32_e64 s[92:93], 31, v212
	s_nop 0
	v_cndmask_b32_e32 v210, 0, v210, vcc
	v_cndmask_b32_e64 v211, 0, v211, s[92:93]
	v_cvt_pk_bf16_f32 v148, v180, v181
	v_cvt_pk_bf16_f32 v149, v182, v183
	v_cvt_pk_bf16_f32 v150, v184, v185
	v_cvt_pk_bf16_f32 v151, v186, v187
	ds_write_b128 v175, v[148:151]
	s_nop 0
	v_cvt_pk_bf16_f32 v148, v188, v189
	v_cvt_pk_bf16_f32 v149, v190, v191
	v_cvt_pk_bf16_f32 v150, v192, v193
	v_cvt_pk_bf16_f32 v151, v194, v195
	ds_write_b128 v175, v[148:151] offset:16
	s_nop 0
	v_cvt_pk_bf16_f32 v148, v196, v197
	v_cvt_pk_bf16_f32 v149, v198, v199
	v_cvt_pk_bf16_f32 v150, v200, v201
	v_cvt_pk_bf16_f32 v151, v202, v203
	ds_write_b128 v175, v[148:151] offset:32
	s_nop 0
	v_cvt_pk_bf16_f32 v148, v204, v205
	v_cvt_pk_bf16_f32 v149, v206, v207
	v_cvt_pk_bf16_f32 v150, v208, v209
	v_cvt_pk_bf16_f32 v151, v210, v211
	ds_write_b128 v175, v[148:151] offset:48
	s_branch .LBB0_1176
